# baseline (speedup 1.0000x reference)
; #define PG8_STAGE(bufoff, gbase, voff) do { _Pragma("unroll") for (int _i = 0; _i < 2; ++_i) \
;         __builtin_amdgcn_global_load_lds((const unsigned*)((const char*)(gbase) + (voff)[_i]), (PG8_LAS unsigned*)(lds + (bufoff) + ldsw + _i * 8192), 16, 0, 0); } while (0)
; #define PG8_LDA(dst, b, h) do { _Pragma("unroll") for (int m = 0; m < 4; ++m) _Pragma("unroll") for (int k = 0; k < 2; ++k) dst[m][k] = *(const PG8_LAS bf16x8*)(lds + PG8_SA(b, h) + aoff + m * 2048 + k * 1024); } while (0)
; #define PG8_LDB(dst, b, h) do { _Pragma("unroll") for (int n = 0; n < 2; ++n) _Pragma("unroll") for (int k = 0; k < 2; ++k) dst[n][k] = *(const PG8_LAS bf16x8*)(lds + PG8_SB(b, h) + boff + n * 2048 + k * 1024); } while (0)
; #define PG8_MMA(ai, bj, At, Bt) do { __builtin_amdgcn_s_setprio(1); _Pragma("unroll") for (int m = 0; m < 4; ++m) _Pragma("unroll") for (int n = 0; n < 2; ++n) _Pragma("unroll") for (int k = 0; k < 2; ++k) \
;         acc[ai][bj][m][n] = __builtin_amdgcn_mfma_f32_16x16x32_bf16(Bt[n][k], At[m][k], acc[ai][bj][m][n], 0, 0, 0); __builtin_amdgcn_s_setprio(0); } while (0)
; #define PG8_WAIT_V(n) asm volatile("s_waitcnt vmcnt(" #n ")" ::: "memory")
; #define PG8_WAIT_L(n) asm volatile("s_waitcnt lgkmcnt(" #n ")" ::: "memory")
; template <class Epi, class Sched, bool ALIGN_EPI = false, bool SP2 = false>
; __device__ __forceinline__ void gemm_phase(PG8_LAS unsigned char* lds, const Gemm g, const Sched& S, const Epi& E, int wid_s_) {
;     ...
;             const bool last = (t == nt - 2);
;             const char* a1 = cA + (size_t)(t + 1) * kstep;
;             const char* a2 = last ? nA : cA + (size_t)(t + 2) * kstep; const char* b2 = last ? nB : cB + (size_t)(t + 2) * kstep;
;             const char* a3 = a2 + kstep; const char* b3 = b2 + kstep;
;             if (last && has_next) S.a_ready(nxt);
;             if constexpr (SP2) {
;             PG8_LDB(B0, 0, 0); PG8_LDB(B1, 0, 1); PG8_SCHED; PG8_LDA(At, 0, 0); PG8_STAGE(PG8_SA(1, 1), a1 + hstep, voffA);
;             PG8_WAIT_V(8); PG8_WAIT_L(0); PG8_BAR; PG8_MMA(0, 0, At, B0); PG8_MMA(0, 1, At, B1); PG8_BAR; PG8_SCHED;
;             PG8_LDA(At, 0, 1); PG8_STAGE(PG8_SB(0, 0), b2, voffB); PG8_STAGE(PG8_SB(0, 1), b2 + hstep, voffB); PG8_STAGE(PG8_SA(0, 0), a2, voffA);
;             PG8_WAIT_V(8); PG8_WAIT_L(0); PG8_BAR; PG8_MMA(1, 0, At, B0); PG8_MMA(1, 1, At, B1); PG8_BAR; PG8_SCHED;
.LBB0_262:
	s_add_i32 s91, s24, 2
	s_add_u32 s14, s2, 0x80
	s_addc_u32 s25, s3, 0
	s_add_i32 s41, 16, 0x10000
	s_cmp_eq_u32 s88, s24
	s_cselect_b32 s25, s21, s25
	s_cselect_b32 s24, s20, s14
	v_add_u32_e32 v96, s41, v147
	s_cselect_b32 s79, s23, vcc_hi
	s_cselect_b32 s78, s22, vcc_lo
	s_add_i32 s14, 16, 0x14000
	ds_read_b128 v[132:135], v96
	ds_read_b128 v[136:139], v96 offset:1024
	ds_read_b128 v[160:163], v96 offset:2048
	ds_read_b128 v[164:167], v96 offset:3072
	v_add_u32_e32 v96, s14, v147
	ds_read_b128 v[168:171], v96
	ds_read_b128 v[172:175], v96 offset:1024
	ds_read_b128 v[176:179], v96 offset:2048
	ds_read_b128 v[180:183], v96 offset:3072
	v_lshl_add_u64 v[98:99], s[2:3], 0, v[156:157]
	s_add_i32 m0, s51, 0xc000
	ds_read_b128 v[194:197], v149
	ds_read_b128 v[198:201], v149 offset:1024
	ds_read_b128 v[202:205], v149 offset:2048
	ds_read_b128 v[206:209], v149 offset:3072
	ds_read_b128 v[210:213], v149 offset:4096
	ds_read_b128 v[214:217], v149 offset:5120
	ds_read_b128 v[218:221], v149 offset:6144
	ds_read_b128 v[222:225], v149 offset:7168
	global_load_lds_dwordx4 v[98:99], off
	v_lshl_add_u64 v[98:99], s[2:3], 0, v[154:155]
	s_add_i32 m0, s51, 0xe000
	s_nop 0
	global_load_lds_dwordx4 v[98:99], off
	s_waitcnt vmcnt(8)
	s_waitcnt lgkmcnt(0)
	s_barrier
	s_setprio 1
	s_waitcnt lgkmcnt(0)
	v_mfma_f32_16x16x32_bf16 v[128:131], v[132:135], v[194:197], v[128:131]
	v_mfma_f32_16x16x32_bf16 v[124:127], v[160:163], v[194:197], v[124:127]
	v_mfma_f32_16x16x32_bf16 v[120:123], v[132:135], v[202:205], v[120:123]
	v_mfma_f32_16x16x32_bf16 v[112:115], v[160:163], v[202:205], v[112:115]
	v_mfma_f32_16x16x32_bf16 v[104:107], v[132:135], v[210:213], v[104:107]
	v_mfma_f32_16x16x32_bf16 v[92:95], v[160:163], v[210:213], v[92:95]
	v_mfma_f32_16x16x32_bf16 v[84:87], v[132:135], v[218:221], v[84:87]
	v_mfma_f32_16x16x32_bf16 v[76:79], v[160:163], v[218:221], v[76:79]
	v_mfma_f32_16x16x32_bf16 v[128:131], v[136:139], v[198:201], v[128:131]
	v_mfma_f32_16x16x32_bf16 v[124:127], v[164:167], v[198:201], v[124:127]
	v_mfma_f32_16x16x32_bf16 v[120:123], v[136:139], v[206:209], v[120:123]
	v_mfma_f32_16x16x32_bf16 v[112:115], v[164:167], v[206:209], v[112:115]
	v_mfma_f32_16x16x32_bf16 v[104:107], v[136:139], v[214:217], v[104:107]
	v_mfma_f32_16x16x32_bf16 v[92:95], v[164:167], v[214:217], v[92:95]
	v_mfma_f32_16x16x32_bf16 v[84:87], v[136:139], v[222:225], v[84:87]
	v_mfma_f32_16x16x32_bf16 v[76:79], v[164:167], v[222:225], v[76:79]
	s_setprio 0
	s_setprio 1
	v_mfma_f32_16x16x32_bf16 v[116:119], v[168:171], v[194:197], v[116:119]
	v_mfma_f32_16x16x32_bf16 v[108:111], v[176:179], v[194:197], v[108:111]
	v_mfma_f32_16x16x32_bf16 v[98:101], v[168:171], v[202:205], v[100:103]
	v_mfma_f32_16x16x32_bf16 v[88:91], v[176:179], v[202:205], v[88:91]
	v_mfma_f32_16x16x32_bf16 v[80:83], v[168:171], v[210:213], v[80:83]
	v_mfma_f32_16x16x32_bf16 v[72:75], v[176:179], v[210:213], v[72:75]
	v_mfma_f32_16x16x32_bf16 v[68:71], v[168:171], v[218:221], v[68:71]
	v_mfma_f32_16x16x32_bf16 v[64:67], v[176:179], v[218:221], v[64:67]
	v_mfma_f32_16x16x32_bf16 v[116:119], v[172:175], v[198:201], v[116:119]
	v_mfma_f32_16x16x32_bf16 v[108:111], v[180:183], v[198:201], v[108:111]
	v_mfma_f32_16x16x32_bf16 v[98:101], v[172:175], v[206:209], v[98:101]
	v_mfma_f32_16x16x32_bf16 v[88:91], v[180:183], v[206:209], v[88:91]
	v_mfma_f32_16x16x32_bf16 v[80:83], v[172:175], v[214:217], v[80:83]
	v_mfma_f32_16x16x32_bf16 v[72:75], v[180:183], v[214:217], v[72:75]
	v_mfma_f32_16x16x32_bf16 v[68:71], v[172:175], v[222:225], v[68:71]
	v_mfma_f32_16x16x32_bf16 v[64:67], v[180:183], v[222:225], v[64:67]
	s_setprio 0
	s_barrier
	s_add_i32 s41, s41, s50
	v_lshl_add_u64 v[150:151], s[78:79], 0, v[142:143]
	s_mov_b32 m0, s41
	ds_read_b128 v[194:197], v149 offset:16384
	ds_read_b128 v[198:201], v149 offset:17408
	ds_read_b128 v[202:205], v149 offset:18432
	ds_read_b128 v[206:209], v149 offset:19456
	ds_read_b128 v[210:213], v149 offset:20480
	ds_read_b128 v[214:217], v149 offset:21504
	ds_read_b128 v[218:221], v149 offset:22528
	ds_read_b128 v[222:225], v149 offset:23552
	global_load_lds_dwordx4 v[150:151], off
	s_add_i32 m0, s41, 0x2000
	v_lshl_add_u64 v[158:159], s[78:79], 0, v[152:153]
	s_add_u32 s78, s78, s10
	s_addc_u32 s79, s79, s11
	s_add_i32 s14, s14, s50
	global_load_lds_dwordx4 v[158:159], off
	v_lshl_add_u64 v[188:189], s[78:79], 0, v[142:143]
	s_mov_b32 m0, s14
	v_lshl_add_u64 v[192:193], s[78:79], 0, v[152:153]
	global_load_lds_dwordx4 v[188:189], off
	s_add_i32 m0, s14, 0x2000
	v_lshl_add_u64 v[226:227], s[24:25], 0, v[140:141]
	global_load_lds_dwordx4 v[192:193], off
	s_mov_b32 m0, s51
	v_lshl_add_u64 v[228:229], s[24:25], 0, v[144:145]
	global_load_lds_dwordx4 v[226:227], off
	s_mov_b32 m0, s80
	s_nop 0
	global_load_lds_dwordx4 v[228:229], off
	s_waitcnt vmcnt(8)
	s_waitcnt lgkmcnt(0)
	s_barrier
; #define PG8_STAGE(bufoff, gbase, voff) do { _Pragma("unroll") for (int _i = 0; _i < 2; ++_i) \
;         __builtin_amdgcn_global_load_lds((const unsigned*)((const char*)(gbase) + (voff)[_i]), (PG8_LAS unsigned*)(lds + (bufoff) + ldsw + _i * 8192), 16, 0, 0); } while (0)
; #define PG8_LDA(dst, b, h) do { _Pragma("unroll") for (int m = 0; m < 4; ++m) _Pragma("unroll") for (int k = 0; k < 2; ++k) dst[m][k] = *(const PG8_LAS bf16x8*)(lds + PG8_SA(b, h) + aoff + m * 2048 + k * 1024); } while (0)
; #define PG8_LDB(dst, b, h) do { _Pragma("unroll") for (int n = 0; n < 2; ++n) _Pragma("unroll") for (int k = 0; k < 2; ++k) dst[n][k] = *(const PG8_LAS bf16x8*)(lds + PG8_SB(b, h) + boff + n * 2048 + k * 1024); } while (0)
; #define PG8_MMA(ai, bj, At, Bt) do { __builtin_amdgcn_s_setprio(1); _Pragma("unroll") for (int m = 0; m < 4; ++m) _Pragma("unroll") for (int n = 0; n < 2; ++n) _Pragma("unroll") for (int k = 0; k < 2; ++k) \
;         acc[ai][bj][m][n] = __builtin_amdgcn_mfma_f32_16x16x32_bf16(Bt[n][k], At[m][k], acc[ai][bj][m][n], 0, 0, 0); __builtin_amdgcn_s_setprio(0); } while (0)
; #define PG8_WAIT_V(n) asm volatile("s_waitcnt vmcnt(" #n ")" ::: "memory")
; #define PG8_WAIT_L(n) asm volatile("s_waitcnt lgkmcnt(" #n ")" ::: "memory")
; #define PG8_BAR __builtin_amdgcn_s_barrier()
; #define PG8_SCHED __builtin_amdgcn_sched_barrier(0)
; template <class Epi, class Sched, bool ALIGN_EPI = false, bool SP2 = false>
; __device__ __forceinline__ void gemm_phase(PG8_LAS unsigned char* lds, const Gemm g, const Sched& S, const Epi& E, int wid_s_) {
;     ...
;             PG8_WAIT_V(8); PG8_WAIT_L(0); PG8_BAR; PG8_MMA(1, 0, At, B0); PG8_MMA(1, 1, At, B1); PG8_BAR; PG8_SCHED;
;             PG8_LDB(B0, 1, 0); PG8_LDB(B1, 1, 1); PG8_SCHED; PG8_LDA(At, 1, 0); PG8_STAGE(PG8_SA(0, 1), a2 + hstep, voffA);
;             PG8_WAIT_V(8); PG8_WAIT_L(0); PG8_BAR; PG8_MMA(0, 0, At, B0); PG8_MMA(0, 1, At, B1); PG8_BAR; PG8_SCHED;
	s_setprio 1
	s_waitcnt lgkmcnt(0)
	v_mfma_f32_16x16x32_bf16 v[60:63], v[132:135], v[194:197], v[60:63]
	v_mfma_f32_16x16x32_bf16 v[56:59], v[160:163], v[194:197], v[56:59]
	v_mfma_f32_16x16x32_bf16 v[52:55], v[132:135], v[202:205], v[52:55]
	v_mfma_f32_16x16x32_bf16 v[48:51], v[160:163], v[202:205], v[48:51]
	v_mfma_f32_16x16x32_bf16 v[36:39], v[132:135], v[210:213], v[36:39]
	v_mfma_f32_16x16x32_bf16 v[32:35], v[160:163], v[210:213], v[32:35]
	v_mfma_f32_16x16x32_bf16 v[20:23], v[132:135], v[218:221], v[20:23]
	v_mfma_f32_16x16x32_bf16 v[16:19], v[160:163], v[218:221], v[16:19]
	v_mfma_f32_16x16x32_bf16 v[60:63], v[136:139], v[198:201], v[60:63]
	v_mfma_f32_16x16x32_bf16 v[56:59], v[164:167], v[198:201], v[56:59]
	v_mfma_f32_16x16x32_bf16 v[52:55], v[136:139], v[206:209], v[52:55]
	v_mfma_f32_16x16x32_bf16 v[48:51], v[164:167], v[206:209], v[48:51]
	v_mfma_f32_16x16x32_bf16 v[36:39], v[136:139], v[214:217], v[36:39]
	v_mfma_f32_16x16x32_bf16 v[32:35], v[164:167], v[214:217], v[32:35]
	v_mfma_f32_16x16x32_bf16 v[20:23], v[136:139], v[222:225], v[20:23]
	v_mfma_f32_16x16x32_bf16 v[16:19], v[164:167], v[222:225], v[16:19]
	s_setprio 0
	s_setprio 1
	v_mfma_f32_16x16x32_bf16 v[44:47], v[168:171], v[194:197], v[44:47]
	v_mfma_f32_16x16x32_bf16 v[40:43], v[176:179], v[194:197], v[40:43]
	v_mfma_f32_16x16x32_bf16 v[28:31], v[168:171], v[202:205], v[28:31]
	v_mfma_f32_16x16x32_bf16 v[24:27], v[176:179], v[202:205], v[24:27]
	v_mfma_f32_16x16x32_bf16 v[12:15], v[168:171], v[210:213], v[12:15]
	v_mfma_f32_16x16x32_bf16 v[8:11], v[176:179], v[210:213], v[8:11]
	v_mfma_f32_16x16x32_bf16 v[4:7], v[168:171], v[218:221], v[4:7]
	v_mfma_f32_16x16x32_bf16 v[0:3], v[176:179], v[218:221], v[0:3]
	v_mfma_f32_16x16x32_bf16 v[44:47], v[172:175], v[198:201], v[44:47]
	v_mfma_f32_16x16x32_bf16 v[40:43], v[180:183], v[198:201], v[40:43]
	v_mfma_f32_16x16x32_bf16 v[28:31], v[172:175], v[206:209], v[28:31]
	v_mfma_f32_16x16x32_bf16 v[24:27], v[180:183], v[206:209], v[24:27]
	v_mfma_f32_16x16x32_bf16 v[12:15], v[172:175], v[214:217], v[12:15]
	v_mfma_f32_16x16x32_bf16 v[8:11], v[180:183], v[214:217], v[8:11]
	v_mfma_f32_16x16x32_bf16 v[4:7], v[172:175], v[222:225], v[4:7]
	v_mfma_f32_16x16x32_bf16 v[0:3], v[180:183], v[222:225], v[0:3]
	s_setprio 0
	s_barrier
	s_add_i32 s14, 16, 0x18000
	v_add_u32_e32 v96, s14, v147
	s_add_i32 s41, 16, 0x1c000
	ds_read_b128 v[132:135], v96
	ds_read_b128 v[136:139], v96 offset:1024
	ds_read_b128 v[160:163], v96 offset:2048
	ds_read_b128 v[164:167], v96 offset:3072
	v_add_u32_e32 v96, s41, v147
	ds_read_b128 v[168:171], v96
	ds_read_b128 v[172:175], v96 offset:1024
	ds_read_b128 v[176:179], v96 offset:2048
	ds_read_b128 v[180:183], v96 offset:3072
	s_add_u32 s24, s24, s10
	s_addc_u32 s25, s25, s11
	s_mov_b32 m0, s81
	v_lshl_add_u64 v[102:103], s[24:25], 0, v[140:141]
	ds_read_b128 v[194:197], v149 offset:32768
	ds_read_b128 v[198:201], v149 offset:33792
	ds_read_b128 v[202:205], v149 offset:34816
	ds_read_b128 v[206:209], v149 offset:35840
	ds_read_b128 v[210:213], v149 offset:36864
	ds_read_b128 v[214:217], v149 offset:37888
	ds_read_b128 v[218:221], v149 offset:38912
	ds_read_b128 v[222:225], v149 offset:39936
	global_load_lds_dwordx4 v[102:103], off
	v_lshl_add_u64 v[102:103], s[24:25], 0, v[144:145]
	s_mov_b32 m0, s82
	s_nop 0
	global_load_lds_dwordx4 v[102:103], off
	s_waitcnt vmcnt(8)
	s_waitcnt lgkmcnt(0)
	s_barrier
	s_setprio 1
	s_waitcnt lgkmcnt(0)
	v_mfma_f32_16x16x32_bf16 v[128:131], v[132:135], v[194:197], v[128:131]
	v_mfma_f32_16x16x32_bf16 v[124:127], v[160:163], v[194:197], v[124:127]
	v_mfma_f32_16x16x32_bf16 v[120:123], v[132:135], v[202:205], v[120:123]
	v_mfma_f32_16x16x32_bf16 v[112:115], v[160:163], v[202:205], v[112:115]
	v_mfma_f32_16x16x32_bf16 v[102:105], v[132:135], v[210:213], v[104:107]
	v_mfma_f32_16x16x32_bf16 v[92:95], v[160:163], v[210:213], v[92:95]
	v_mfma_f32_16x16x32_bf16 v[84:87], v[132:135], v[218:221], v[84:87]
	v_mfma_f32_16x16x32_bf16 v[76:79], v[160:163], v[218:221], v[76:79]
	v_mfma_f32_16x16x32_bf16 v[128:131], v[136:139], v[198:201], v[128:131]
	v_mfma_f32_16x16x32_bf16 v[124:127], v[164:167], v[198:201], v[124:127]
	v_mfma_f32_16x16x32_bf16 v[120:123], v[136:139], v[206:209], v[120:123]
	v_mfma_f32_16x16x32_bf16 v[112:115], v[164:167], v[206:209], v[112:115]
	v_mfma_f32_16x16x32_bf16 v[104:107], v[136:139], v[214:217], v[102:105]
	v_mfma_f32_16x16x32_bf16 v[92:95], v[164:167], v[214:217], v[92:95]
	v_mfma_f32_16x16x32_bf16 v[84:87], v[136:139], v[222:225], v[84:87]
	v_mfma_f32_16x16x32_bf16 v[76:79], v[164:167], v[222:225], v[76:79]
	s_setprio 0
	s_setprio 1
	v_mfma_f32_16x16x32_bf16 v[116:119], v[168:171], v[194:197], v[116:119]
	v_mfma_f32_16x16x32_bf16 v[108:111], v[176:179], v[194:197], v[108:111]
	v_mfma_f32_16x16x32_bf16 v[98:101], v[168:171], v[202:205], v[98:101]
	v_mfma_f32_16x16x32_bf16 v[88:91], v[176:179], v[202:205], v[88:91]
	v_mfma_f32_16x16x32_bf16 v[80:83], v[168:171], v[210:213], v[80:83]
	v_mfma_f32_16x16x32_bf16 v[72:75], v[176:179], v[210:213], v[72:75]
	v_mfma_f32_16x16x32_bf16 v[68:71], v[168:171], v[218:221], v[68:71]
	v_mfma_f32_16x16x32_bf16 v[64:67], v[176:179], v[218:221], v[64:67]
	v_mfma_f32_16x16x32_bf16 v[116:119], v[172:175], v[198:201], v[116:119]
	v_mfma_f32_16x16x32_bf16 v[108:111], v[180:183], v[198:201], v[108:111]
	v_mfma_f32_16x16x32_bf16 v[100:103], v[172:175], v[206:209], v[98:101]
	v_mfma_f32_16x16x32_bf16 v[88:91], v[180:183], v[206:209], v[88:91]
	v_mfma_f32_16x16x32_bf16 v[80:83], v[172:175], v[214:217], v[80:83]
	v_mfma_f32_16x16x32_bf16 v[72:75], v[180:183], v[214:217], v[72:75]
	v_mfma_f32_16x16x32_bf16 v[68:71], v[172:175], v[222:225], v[68:71]
	v_mfma_f32_16x16x32_bf16 v[64:67], v[180:183], v[222:225], v[64:67]
	s_setprio 0
	s_barrier
; #define PG8_STAGE(bufoff, gbase, voff) do { _Pragma("unroll") for (int _i = 0; _i < 2; ++_i) \
;         __builtin_amdgcn_global_load_lds((const unsigned*)((const char*)(gbase) + (voff)[_i]), (PG8_LAS unsigned*)(lds + (bufoff) + ldsw + _i * 8192), 16, 0, 0); } while (0)
; #define PG8_LDA(dst, b, h) do { _Pragma("unroll") for (int m = 0; m < 4; ++m) _Pragma("unroll") for (int k = 0; k < 2; ++k) dst[m][k] = *(const PG8_LAS bf16x8*)(lds + PG8_SA(b, h) + aoff + m * 2048 + k * 1024); } while (0)
; #define PG8_MMA(ai, bj, At, Bt) do { __builtin_amdgcn_s_setprio(1); _Pragma("unroll") for (int m = 0; m < 4; ++m) _Pragma("unroll") for (int n = 0; n < 2; ++n) _Pragma("unroll") for (int k = 0; k < 2; ++k) \
;         acc[ai][bj][m][n] = __builtin_amdgcn_mfma_f32_16x16x32_bf16(Bt[n][k], At[m][k], acc[ai][bj][m][n], 0, 0, 0); __builtin_amdgcn_s_setprio(0); } while (0)
; #define PG8_WAIT_V(n) asm volatile("s_waitcnt vmcnt(" #n ")" ::: "memory")
; #define PG8_WAIT_L(n) asm volatile("s_waitcnt lgkmcnt(" #n ")" ::: "memory")
; #define PG8_BAR __builtin_amdgcn_s_barrier()
; #define PG8_SCHED __builtin_amdgcn_sched_barrier(0)
; template <class Epi, class Sched, bool ALIGN_EPI = false, bool SP2 = false>
; __device__ __forceinline__ void gemm_phase(PG8_LAS unsigned char* lds, const Gemm g, const Sched& S, const Epi& E, int wid_s_) {
;     ...
;         for (int t = 0; t < nt; t += 2) {
;             const bool last = (t == nt - 2);
;             const char* a1 = cA + (size_t)(t + 1) * kstep;
;             const char* a2 = last ? nA : cA + (size_t)(t + 2) * kstep; const char* b2 = last ? nB : cB + (size_t)(t + 2) * kstep;
;     ...
;             PG8_LDA(At, 1, 1); PG8_STAGE(PG8_SB(1, 0), b3, voffB); PG8_STAGE(PG8_SB(1, 1), b3 + hstep, voffB); PG8_STAGE(PG8_SA(1, 0), a3, voffA);
;             PG8_WAIT_V(8); PG8_WAIT_L(0); PG8_BAR; PG8_MMA(1, 0, At, B0); PG8_MMA(1, 1, At, B1); PG8_BAR; PG8_SCHED;
	s_add_i32 s14, s14, s50
	v_lshl_add_u64 v[98:99], v[150:151], 0, s[42:43]
	s_mov_b32 m0, s14
	ds_read_b128 v[194:197], v149 offset:49152
	ds_read_b128 v[198:201], v149 offset:50176
	ds_read_b128 v[202:205], v149 offset:51200
	ds_read_b128 v[206:209], v149 offset:52224
	ds_read_b128 v[210:213], v149 offset:53248
	ds_read_b128 v[214:217], v149 offset:54272
	ds_read_b128 v[218:221], v149 offset:55296
	ds_read_b128 v[222:225], v149 offset:56320
	global_load_lds_dwordx4 v[98:99], off
	v_lshl_add_u64 v[98:99], v[158:159], 0, s[42:43]
	s_add_i32 m0, s14, 0x2000
	s_add_i32 s14, s41, s50
	global_load_lds_dwordx4 v[98:99], off
	v_lshl_add_u64 v[98:99], v[188:189], 0, s[42:43]
	s_mov_b32 m0, s14
	s_nop 0
	global_load_lds_dwordx4 v[98:99], off
	v_lshl_add_u64 v[98:99], v[192:193], 0, s[42:43]
	s_add_i32 m0, s14, 0x2000
	s_nop 0
	global_load_lds_dwordx4 v[98:99], off
	v_lshl_add_u64 v[98:99], v[226:227], 0, s[42:43]
	s_mov_b32 m0, s85
	s_nop 0
	global_load_lds_dwordx4 v[98:99], off
	v_lshl_add_u64 v[98:99], v[228:229], 0, s[42:43]
	s_mov_b32 m0, s86
	s_nop 0
	global_load_lds_dwordx4 v[98:99], off
	s_waitcnt vmcnt(8)
	s_waitcnt lgkmcnt(0)
	s_barrier
	s_setprio 1
	s_waitcnt lgkmcnt(0)
	v_mfma_f32_16x16x32_bf16 v[60:63], v[132:135], v[194:197], v[60:63]
	v_mfma_f32_16x16x32_bf16 v[56:59], v[160:163], v[194:197], v[56:59]
	v_mfma_f32_16x16x32_bf16 v[52:55], v[132:135], v[202:205], v[52:55]
	v_mfma_f32_16x16x32_bf16 v[48:51], v[160:163], v[202:205], v[48:51]
	v_mfma_f32_16x16x32_bf16 v[36:39], v[132:135], v[210:213], v[36:39]
	v_mfma_f32_16x16x32_bf16 v[32:35], v[160:163], v[210:213], v[32:35]
	v_mfma_f32_16x16x32_bf16 v[20:23], v[132:135], v[218:221], v[20:23]
	v_mfma_f32_16x16x32_bf16 v[16:19], v[160:163], v[218:221], v[16:19]
	v_mfma_f32_16x16x32_bf16 v[60:63], v[136:139], v[198:201], v[60:63]
	v_mfma_f32_16x16x32_bf16 v[56:59], v[164:167], v[198:201], v[56:59]
	v_mfma_f32_16x16x32_bf16 v[52:55], v[136:139], v[206:209], v[52:55]
	v_mfma_f32_16x16x32_bf16 v[48:51], v[164:167], v[206:209], v[48:51]
	v_mfma_f32_16x16x32_bf16 v[36:39], v[136:139], v[214:217], v[36:39]
	v_mfma_f32_16x16x32_bf16 v[32:35], v[164:167], v[214:217], v[32:35]
	v_mfma_f32_16x16x32_bf16 v[20:23], v[136:139], v[222:225], v[20:23]
	v_mfma_f32_16x16x32_bf16 v[16:19], v[164:167], v[222:225], v[16:19]
	s_setprio 0
	s_setprio 1
	v_mfma_f32_16x16x32_bf16 v[44:47], v[168:171], v[194:197], v[44:47]
	v_mfma_f32_16x16x32_bf16 v[40:43], v[176:179], v[194:197], v[40:43]
	v_mfma_f32_16x16x32_bf16 v[28:31], v[168:171], v[202:205], v[28:31]
	v_mfma_f32_16x16x32_bf16 v[24:27], v[176:179], v[202:205], v[24:27]
	v_mfma_f32_16x16x32_bf16 v[12:15], v[168:171], v[210:213], v[12:15]
	v_mfma_f32_16x16x32_bf16 v[8:11], v[176:179], v[210:213], v[8:11]
	v_mfma_f32_16x16x32_bf16 v[4:7], v[168:171], v[218:221], v[4:7]
	v_mfma_f32_16x16x32_bf16 v[0:3], v[176:179], v[218:221], v[0:3]
	v_mfma_f32_16x16x32_bf16 v[44:47], v[172:175], v[198:201], v[44:47]
	v_mfma_f32_16x16x32_bf16 v[40:43], v[180:183], v[198:201], v[40:43]
	v_mfma_f32_16x16x32_bf16 v[28:31], v[172:175], v[206:209], v[28:31]
	v_mfma_f32_16x16x32_bf16 v[24:27], v[180:183], v[206:209], v[24:27]
	v_mfma_f32_16x16x32_bf16 v[12:15], v[172:175], v[214:217], v[12:15]
	v_mfma_f32_16x16x32_bf16 v[8:11], v[180:183], v[214:217], v[8:11]
	v_mfma_f32_16x16x32_bf16 v[4:7], v[172:175], v[222:225], v[4:7]
	v_mfma_f32_16x16x32_bf16 v[0:3], v[180:183], v[222:225], v[0:3]
	s_setprio 0
	s_barrier
	s_add_u32 vcc_lo, vcc_lo, 0x100
	s_addc_u32 vcc_hi, vcc_hi, 0
	s_add_u32 s2, s2, 0x100
	s_addc_u32 s3, s3, 0
	s_cmp_ge_i32 s91, s87
	s_mov_b32 s24, s91
	s_cbranch_scc0 .LBB0_262
	v_add_u32_e32 v192, 64, v191
	s_and_b64 vcc, exec, s[18:19]
	s_cbranch_vccnz .LBB0_267
	s_branch .LBB0_268

; #define PG8_STAGE(bufoff, gbase, voff) do { _Pragma("unroll") for (int _i = 0; _i < 2; ++_i) \
;         __builtin_amdgcn_global_load_lds((const unsigned*)((const char*)(gbase) + (voff)[_i]), (PG8_LAS unsigned*)(lds + (bufoff) + ldsw + _i * 8192), 16, 0, 0); } while (0)
; #define PG8_LDA(dst, b, h) do { _Pragma("unroll") for (int m = 0; m < 4; ++m) _Pragma("unroll") for (int k = 0; k < 2; ++k) dst[m][k] = *(const PG8_LAS bf16x8*)(lds + PG8_SA(b, h) + aoff + m * 2048 + k * 1024); } while (0)
; #define PG8_LDB(dst, b, h) do { _Pragma("unroll") for (int n = 0; n < 2; ++n) _Pragma("unroll") for (int k = 0; k < 2; ++k) dst[n][k] = *(const PG8_LAS bf16x8*)(lds + PG8_SB(b, h) + boff + n * 2048 + k * 1024); } while (0)
; #define PG8_MMA(ai, bj, At, Bt) do { __builtin_amdgcn_s_setprio(1); _Pragma("unroll") for (int m = 0; m < 4; ++m) _Pragma("unroll") for (int n = 0; n < 2; ++n) _Pragma("unroll") for (int k = 0; k < 2; ++k) \
;         acc[ai][bj][m][n] = __builtin_amdgcn_mfma_f32_16x16x32_bf16(Bt[n][k], At[m][k], acc[ai][bj][m][n], 0, 0, 0); __builtin_amdgcn_s_setprio(0); } while (0)
; #define PG8_WAIT_V(n) asm volatile("s_waitcnt vmcnt(" #n ")" ::: "memory")
; #define PG8_WAIT_L(n) asm volatile("s_waitcnt lgkmcnt(" #n ")" ::: "memory")
; template <class Epi, class Sched, bool ALIGN_EPI = false, bool SP2 = false>
; __device__ __forceinline__ void gemm_phase(PG8_LAS unsigned char* lds, const Gemm g, const Sched& S, const Epi& E, int wid_s_) {
;     ...
;             const bool last = (t == nt - 2);
;             const char* a1 = cA + (size_t)(t + 1) * kstep;
;             const char* a2 = last ? nA : cA + (size_t)(t + 2) * kstep; const char* b2 = last ? nB : cB + (size_t)(t + 2) * kstep;
;             const char* a3 = a2 + kstep; const char* b3 = b2 + kstep;
;             if (last && has_next) S.a_ready(nxt);
;             if constexpr (SP2) {
;             PG8_LDB(B0, 0, 0); PG8_LDB(B1, 0, 1); PG8_SCHED; PG8_LDA(At, 0, 0); PG8_STAGE(PG8_SA(1, 1), a1 + hstep, voffA);
;             PG8_WAIT_V(8); PG8_WAIT_L(0); PG8_BAR; PG8_MMA(0, 0, At, B0); PG8_MMA(0, 1, At, B1); PG8_BAR; PG8_SCHED;
;             PG8_LDA(At, 0, 1); PG8_STAGE(PG8_SB(0, 0), b2, voffB); PG8_STAGE(PG8_SB(0, 1), b2 + hstep, voffB); PG8_STAGE(PG8_SA(0, 0), a2, voffA);
;             PG8_WAIT_V(8); PG8_WAIT_L(0); PG8_BAR; PG8_MMA(1, 0, At, B0); PG8_MMA(1, 1, At, B1); PG8_BAR; PG8_SCHED;
.LBB0_628:
	s_add_i32 s84, s48, 2
	s_add_u32 s78, s2, 0x80
	s_addc_u32 s49, s3, 0
	s_add_i32 s85, 16, 0x10000
	s_cmp_eq_u32 s5, s48
	s_cselect_b32 s49, s81, s49
	s_cselect_b32 s48, s80, s78
	v_add_u32_e32 v150, s85, v147
	s_cselect_b32 s79, s83, vcc_hi
	s_cselect_b32 s78, s82, vcc_lo
	s_add_i32 s20, 16, 0x14000
	ds_read_b128 v[122:125], v150
	ds_read_b128 v[126:129], v150 offset:1024
	ds_read_b128 v[154:157], v150 offset:2048
	ds_read_b128 v[158:161], v150 offset:3072
	v_add_u32_e32 v150, s20, v147
	ds_read_b128 v[162:165], v150
	ds_read_b128 v[166:169], v150 offset:1024
	ds_read_b128 v[170:173], v150 offset:2048
	ds_read_b128 v[174:177], v150 offset:3072
	v_lshl_add_u64 v[150:151], s[2:3], 0, v[152:153]
	s_add_i32 m0, s51, 0xc000
	ds_read_b128 v[180:183], v149
	ds_read_b128 v[196:199], v149 offset:1024
	ds_read_b128 v[200:203], v149 offset:2048
	ds_read_b128 v[204:207], v149 offset:3072
	ds_read_b128 v[208:211], v149 offset:4096
	ds_read_b128 v[212:215], v149 offset:5120
	ds_read_b128 v[216:219], v149 offset:6144
	ds_read_b128 v[220:223], v149 offset:7168
	global_load_lds_dwordx4 v[150:151], off
	v_lshl_add_u64 v[150:151], s[2:3], 0, v[144:145]
	s_add_i32 m0, s51, 0xe000
	s_nop 0
	global_load_lds_dwordx4 v[150:151], off
	s_waitcnt vmcnt(8)
	s_waitcnt lgkmcnt(0)
	s_barrier
	s_setprio 1
	s_waitcnt lgkmcnt(0)
	v_mfma_f32_16x16x32_bf16 v[134:137], v[122:125], v[180:183], v[134:137]
	v_mfma_f32_16x16x32_bf16 v[130:133], v[154:157], v[180:183], v[130:133]
	v_mfma_f32_16x16x32_bf16 v[118:121], v[122:125], v[200:203], v[118:121]
	v_mfma_f32_16x16x32_bf16 v[114:117], v[154:157], v[200:203], v[114:117]
	v_mfma_f32_16x16x32_bf16 v[110:113], v[122:125], v[208:211], v[110:113]
	v_mfma_f32_16x16x32_bf16 v[106:109], v[154:157], v[208:211], v[106:109]
	v_mfma_f32_16x16x32_bf16 v[102:105], v[122:125], v[216:219], v[102:105]
	v_mfma_f32_16x16x32_bf16 v[98:101], v[154:157], v[216:219], v[98:101]
	v_mfma_f32_16x16x32_bf16 v[134:137], v[126:129], v[196:199], v[134:137]
	v_mfma_f32_16x16x32_bf16 v[130:133], v[158:161], v[196:199], v[130:133]
	v_mfma_f32_16x16x32_bf16 v[118:121], v[126:129], v[204:207], v[118:121]
	v_mfma_f32_16x16x32_bf16 v[114:117], v[158:161], v[204:207], v[114:117]
	v_mfma_f32_16x16x32_bf16 v[110:113], v[126:129], v[212:215], v[110:113]
	v_mfma_f32_16x16x32_bf16 v[106:109], v[158:161], v[212:215], v[106:109]
	v_mfma_f32_16x16x32_bf16 v[102:105], v[126:129], v[220:223], v[102:105]
	v_mfma_f32_16x16x32_bf16 v[98:101], v[158:161], v[220:223], v[98:101]
	s_setprio 0
	s_setprio 1
	v_mfma_f32_16x16x32_bf16 v[60:63], v[162:165], v[180:183], v[60:63]
	v_mfma_f32_16x16x32_bf16 v[56:59], v[170:173], v[180:183], v[56:59]
	v_mfma_f32_16x16x32_bf16 v[52:55], v[162:165], v[200:203], v[52:55]
	v_mfma_f32_16x16x32_bf16 v[48:51], v[170:173], v[200:203], v[48:51]
	v_mfma_f32_16x16x32_bf16 v[44:47], v[162:165], v[208:211], v[44:47]
	v_mfma_f32_16x16x32_bf16 v[40:43], v[170:173], v[208:211], v[40:43]
	v_mfma_f32_16x16x32_bf16 v[36:39], v[162:165], v[216:219], v[36:39]
	v_mfma_f32_16x16x32_bf16 v[32:35], v[170:173], v[216:219], v[32:35]
	v_mfma_f32_16x16x32_bf16 v[60:63], v[166:169], v[196:199], v[60:63]
	v_mfma_f32_16x16x32_bf16 v[56:59], v[174:177], v[196:199], v[56:59]
	v_mfma_f32_16x16x32_bf16 v[52:55], v[166:169], v[204:207], v[52:55]
	v_mfma_f32_16x16x32_bf16 v[48:51], v[174:177], v[204:207], v[48:51]
	v_mfma_f32_16x16x32_bf16 v[44:47], v[166:169], v[212:215], v[44:47]
	v_mfma_f32_16x16x32_bf16 v[40:43], v[174:177], v[212:215], v[40:43]
	v_mfma_f32_16x16x32_bf16 v[36:39], v[166:169], v[220:223], v[36:39]
	v_mfma_f32_16x16x32_bf16 v[32:35], v[174:177], v[220:223], v[32:35]
	s_setprio 0
	s_barrier
	s_add_i32 s21, s85, s50
	v_lshl_add_u64 v[150:151], s[78:79], 0, v[96:97]
	s_mov_b32 m0, s21
	ds_read_b128 v[180:183], v149 offset:16384
	ds_read_b128 v[196:199], v149 offset:17408
	ds_read_b128 v[200:203], v149 offset:18432
	ds_read_b128 v[204:207], v149 offset:19456
	ds_read_b128 v[208:211], v149 offset:20480
	ds_read_b128 v[212:215], v149 offset:21504
	ds_read_b128 v[216:219], v149 offset:22528
	ds_read_b128 v[220:223], v149 offset:23552
	global_load_lds_dwordx4 v[150:151], off
	s_add_i32 m0, s21, 0x2000
	v_lshl_add_u64 v[178:179], s[78:79], 0, v[142:143]
	s_add_u32 s78, s78, s10
	s_addc_u32 s79, s79, s11
	s_add_i32 s20, s20, s50
	global_load_lds_dwordx4 v[178:179], off
	v_lshl_add_u64 v[188:189], s[78:79], 0, v[96:97]
	s_mov_b32 m0, s20
	v_lshl_add_u64 v[192:193], s[78:79], 0, v[142:143]
	global_load_lds_dwordx4 v[188:189], off
	s_add_i32 m0, s20, 0x2000
	v_lshl_add_u64 v[194:195], s[48:49], 0, v[138:139]
	global_load_lds_dwordx4 v[192:193], off
	s_mov_b32 m0, s51
	v_lshl_add_u64 v[224:225], s[48:49], 0, v[140:141]
	global_load_lds_dwordx4 v[194:195], off
	s_mov_b32 m0, s86
	s_nop 0
	global_load_lds_dwordx4 v[224:225], off
	s_waitcnt vmcnt(8)
	s_waitcnt lgkmcnt(0)
	s_barrier
; #define PG8_STAGE(bufoff, gbase, voff) do { _Pragma("unroll") for (int _i = 0; _i < 2; ++_i) \
;         __builtin_amdgcn_global_load_lds((const unsigned*)((const char*)(gbase) + (voff)[_i]), (PG8_LAS unsigned*)(lds + (bufoff) + ldsw + _i * 8192), 16, 0, 0); } while (0)
; #define PG8_LDA(dst, b, h) do { _Pragma("unroll") for (int m = 0; m < 4; ++m) _Pragma("unroll") for (int k = 0; k < 2; ++k) dst[m][k] = *(const PG8_LAS bf16x8*)(lds + PG8_SA(b, h) + aoff + m * 2048 + k * 1024); } while (0)
; #define PG8_LDB(dst, b, h) do { _Pragma("unroll") for (int n = 0; n < 2; ++n) _Pragma("unroll") for (int k = 0; k < 2; ++k) dst[n][k] = *(const PG8_LAS bf16x8*)(lds + PG8_SB(b, h) + boff + n * 2048 + k * 1024); } while (0)
; #define PG8_MMA(ai, bj, At, Bt) do { __builtin_amdgcn_s_setprio(1); _Pragma("unroll") for (int m = 0; m < 4; ++m) _Pragma("unroll") for (int n = 0; n < 2; ++n) _Pragma("unroll") for (int k = 0; k < 2; ++k) \
;         acc[ai][bj][m][n] = __builtin_amdgcn_mfma_f32_16x16x32_bf16(Bt[n][k], At[m][k], acc[ai][bj][m][n], 0, 0, 0); __builtin_amdgcn_s_setprio(0); } while (0)
; #define PG8_WAIT_V(n) asm volatile("s_waitcnt vmcnt(" #n ")" ::: "memory")
; #define PG8_WAIT_L(n) asm volatile("s_waitcnt lgkmcnt(" #n ")" ::: "memory")
; #define PG8_BAR __builtin_amdgcn_s_barrier()
; #define PG8_SCHED __builtin_amdgcn_sched_barrier(0)
; template <class Epi, class Sched, bool ALIGN_EPI = false, bool SP2 = false>
; __device__ __forceinline__ void gemm_phase(PG8_LAS unsigned char* lds, const Gemm g, const Sched& S, const Epi& E, int wid_s_) {
;     ...
;             PG8_WAIT_V(8); PG8_WAIT_L(0); PG8_BAR; PG8_MMA(1, 0, At, B0); PG8_MMA(1, 1, At, B1); PG8_BAR; PG8_SCHED;
;             PG8_LDB(B0, 1, 0); PG8_LDB(B1, 1, 1); PG8_SCHED; PG8_LDA(At, 1, 0); PG8_STAGE(PG8_SA(0, 1), a2 + hstep, voffA);
;             PG8_WAIT_V(8); PG8_WAIT_L(0); PG8_BAR; PG8_MMA(0, 0, At, B0); PG8_MMA(0, 1, At, B1); PG8_BAR; PG8_SCHED;
	s_setprio 1
	s_waitcnt lgkmcnt(0)
	v_mfma_f32_16x16x32_bf16 v[92:95], v[122:125], v[180:183], v[92:95]
	v_mfma_f32_16x16x32_bf16 v[88:91], v[154:157], v[180:183], v[88:91]
	v_mfma_f32_16x16x32_bf16 v[84:87], v[122:125], v[200:203], v[84:87]
	v_mfma_f32_16x16x32_bf16 v[80:83], v[154:157], v[200:203], v[80:83]
	v_mfma_f32_16x16x32_bf16 v[76:79], v[122:125], v[208:211], v[76:79]
	v_mfma_f32_16x16x32_bf16 v[72:75], v[154:157], v[208:211], v[72:75]
	v_mfma_f32_16x16x32_bf16 v[68:71], v[122:125], v[216:219], v[68:71]
	v_mfma_f32_16x16x32_bf16 v[64:67], v[154:157], v[216:219], v[64:67]
	v_mfma_f32_16x16x32_bf16 v[92:95], v[126:129], v[196:199], v[92:95]
	v_mfma_f32_16x16x32_bf16 v[88:91], v[158:161], v[196:199], v[88:91]
	v_mfma_f32_16x16x32_bf16 v[84:87], v[126:129], v[204:207], v[84:87]
	v_mfma_f32_16x16x32_bf16 v[80:83], v[158:161], v[204:207], v[80:83]
	v_mfma_f32_16x16x32_bf16 v[76:79], v[126:129], v[212:215], v[76:79]
	v_mfma_f32_16x16x32_bf16 v[72:75], v[158:161], v[212:215], v[72:75]
	v_mfma_f32_16x16x32_bf16 v[68:71], v[126:129], v[220:223], v[68:71]
	v_mfma_f32_16x16x32_bf16 v[64:67], v[158:161], v[220:223], v[64:67]
	s_setprio 0
	s_setprio 1
	v_mfma_f32_16x16x32_bf16 v[28:31], v[162:165], v[180:183], v[28:31]
	v_mfma_f32_16x16x32_bf16 v[24:27], v[170:173], v[180:183], v[24:27]
	v_mfma_f32_16x16x32_bf16 v[20:23], v[162:165], v[200:203], v[20:23]
	v_mfma_f32_16x16x32_bf16 v[16:19], v[170:173], v[200:203], v[16:19]
	v_mfma_f32_16x16x32_bf16 v[12:15], v[162:165], v[208:211], v[12:15]
	v_mfma_f32_16x16x32_bf16 v[8:11], v[170:173], v[208:211], v[8:11]
	v_mfma_f32_16x16x32_bf16 v[4:7], v[162:165], v[216:219], v[4:7]
	v_mfma_f32_16x16x32_bf16 v[0:3], v[170:173], v[216:219], v[0:3]
	v_mfma_f32_16x16x32_bf16 v[28:31], v[166:169], v[196:199], v[28:31]
	v_mfma_f32_16x16x32_bf16 v[24:27], v[174:177], v[196:199], v[24:27]
	v_mfma_f32_16x16x32_bf16 v[20:23], v[166:169], v[204:207], v[20:23]
	v_mfma_f32_16x16x32_bf16 v[16:19], v[174:177], v[204:207], v[16:19]
	v_mfma_f32_16x16x32_bf16 v[12:15], v[166:169], v[212:215], v[12:15]
	v_mfma_f32_16x16x32_bf16 v[8:11], v[174:177], v[212:215], v[8:11]
	v_mfma_f32_16x16x32_bf16 v[4:7], v[166:169], v[220:223], v[4:7]
	v_mfma_f32_16x16x32_bf16 v[0:3], v[174:177], v[220:223], v[0:3]
	s_setprio 0
	s_barrier
	s_add_i32 s20, 16, 0x18000
	s_add_i32 s21, 16, 0x1c000
	v_add_u32_e32 v158, s20, v147
	v_add_u32_e32 v174, s21, v147
	ds_read_b128 v[122:125], v158
	ds_read_b128 v[126:129], v158 offset:1024
	ds_read_b128 v[154:157], v158 offset:2048
	ds_read_b128 v[158:161], v158 offset:3072
	ds_read_b128 v[162:165], v174
	ds_read_b128 v[166:169], v174 offset:1024
	ds_read_b128 v[170:173], v174 offset:2048
	ds_read_b128 v[174:177], v174 offset:3072
	s_add_u32 s48, s48, s10
	s_addc_u32 s49, s49, s11
	s_mov_b32 m0, s87
	v_lshl_add_u64 v[226:227], s[48:49], 0, v[138:139]
	ds_read_b128 v[180:183], v149 offset:32768
	ds_read_b128 v[196:199], v149 offset:33792
	ds_read_b128 v[200:203], v149 offset:34816
	ds_read_b128 v[204:207], v149 offset:35840
	ds_read_b128 v[208:211], v149 offset:36864
	ds_read_b128 v[212:215], v149 offset:37888
	ds_read_b128 v[216:219], v149 offset:38912
	ds_read_b128 v[220:223], v149 offset:39936
	global_load_lds_dwordx4 v[226:227], off
	v_lshl_add_u64 v[226:227], s[48:49], 0, v[140:141]
	s_mov_b32 m0, s88
	s_nop 0
	global_load_lds_dwordx4 v[226:227], off
	s_waitcnt vmcnt(8)
	s_waitcnt lgkmcnt(0)
	s_barrier
	s_setprio 1
	s_waitcnt lgkmcnt(0)
	v_mfma_f32_16x16x32_bf16 v[134:137], v[122:125], v[180:183], v[134:137]
	v_mfma_f32_16x16x32_bf16 v[130:133], v[154:157], v[180:183], v[130:133]
	v_mfma_f32_16x16x32_bf16 v[118:121], v[122:125], v[200:203], v[118:121]
	v_mfma_f32_16x16x32_bf16 v[114:117], v[154:157], v[200:203], v[114:117]
	v_mfma_f32_16x16x32_bf16 v[110:113], v[122:125], v[208:211], v[110:113]
	v_mfma_f32_16x16x32_bf16 v[106:109], v[154:157], v[208:211], v[106:109]
	v_mfma_f32_16x16x32_bf16 v[102:105], v[122:125], v[216:219], v[102:105]
	v_mfma_f32_16x16x32_bf16 v[98:101], v[154:157], v[216:219], v[98:101]
	v_mfma_f32_16x16x32_bf16 v[134:137], v[126:129], v[196:199], v[134:137]
	v_mfma_f32_16x16x32_bf16 v[130:133], v[158:161], v[196:199], v[130:133]
	v_mfma_f32_16x16x32_bf16 v[118:121], v[126:129], v[204:207], v[118:121]
	v_mfma_f32_16x16x32_bf16 v[114:117], v[158:161], v[204:207], v[114:117]
	v_mfma_f32_16x16x32_bf16 v[110:113], v[126:129], v[212:215], v[110:113]
	v_mfma_f32_16x16x32_bf16 v[106:109], v[158:161], v[212:215], v[106:109]
	v_mfma_f32_16x16x32_bf16 v[102:105], v[126:129], v[220:223], v[102:105]
	v_mfma_f32_16x16x32_bf16 v[98:101], v[158:161], v[220:223], v[98:101]
	s_setprio 0
	s_setprio 1
	v_mfma_f32_16x16x32_bf16 v[60:63], v[162:165], v[180:183], v[60:63]
	v_mfma_f32_16x16x32_bf16 v[56:59], v[170:173], v[180:183], v[56:59]
	v_mfma_f32_16x16x32_bf16 v[52:55], v[162:165], v[200:203], v[52:55]
	v_mfma_f32_16x16x32_bf16 v[48:51], v[170:173], v[200:203], v[48:51]
	v_mfma_f32_16x16x32_bf16 v[44:47], v[162:165], v[208:211], v[44:47]
	v_mfma_f32_16x16x32_bf16 v[40:43], v[170:173], v[208:211], v[40:43]
	v_mfma_f32_16x16x32_bf16 v[36:39], v[162:165], v[216:219], v[36:39]
	v_mfma_f32_16x16x32_bf16 v[32:35], v[170:173], v[216:219], v[32:35]
	v_mfma_f32_16x16x32_bf16 v[60:63], v[166:169], v[196:199], v[60:63]
	v_mfma_f32_16x16x32_bf16 v[56:59], v[174:177], v[196:199], v[56:59]
	v_mfma_f32_16x16x32_bf16 v[52:55], v[166:169], v[204:207], v[52:55]
	v_mfma_f32_16x16x32_bf16 v[48:51], v[174:177], v[204:207], v[48:51]
	v_mfma_f32_16x16x32_bf16 v[44:47], v[166:169], v[212:215], v[44:47]
	v_mfma_f32_16x16x32_bf16 v[40:43], v[174:177], v[212:215], v[40:43]
	v_mfma_f32_16x16x32_bf16 v[36:39], v[166:169], v[220:223], v[36:39]
	v_mfma_f32_16x16x32_bf16 v[32:35], v[174:177], v[220:223], v[32:35]
	s_setprio 0
	s_barrier
; #define PG8_STAGE(bufoff, gbase, voff) do { _Pragma("unroll") for (int _i = 0; _i < 2; ++_i) \
;         __builtin_amdgcn_global_load_lds((const unsigned*)((const char*)(gbase) + (voff)[_i]), (PG8_LAS unsigned*)(lds + (bufoff) + ldsw + _i * 8192), 16, 0, 0); } while (0)
; #define PG8_LDA(dst, b, h) do { _Pragma("unroll") for (int m = 0; m < 4; ++m) _Pragma("unroll") for (int k = 0; k < 2; ++k) dst[m][k] = *(const PG8_LAS bf16x8*)(lds + PG8_SA(b, h) + aoff + m * 2048 + k * 1024); } while (0)
; #define PG8_MMA(ai, bj, At, Bt) do { __builtin_amdgcn_s_setprio(1); _Pragma("unroll") for (int m = 0; m < 4; ++m) _Pragma("unroll") for (int n = 0; n < 2; ++n) _Pragma("unroll") for (int k = 0; k < 2; ++k) \
;         acc[ai][bj][m][n] = __builtin_amdgcn_mfma_f32_16x16x32_bf16(Bt[n][k], At[m][k], acc[ai][bj][m][n], 0, 0, 0); __builtin_amdgcn_s_setprio(0); } while (0)
; #define PG8_WAIT_V(n) asm volatile("s_waitcnt vmcnt(" #n ")" ::: "memory")
; #define PG8_WAIT_L(n) asm volatile("s_waitcnt lgkmcnt(" #n ")" ::: "memory")
; #define PG8_BAR __builtin_amdgcn_s_barrier()
; #define PG8_SCHED __builtin_amdgcn_sched_barrier(0)
; template <class Epi, class Sched, bool ALIGN_EPI = false, bool SP2 = false>
; __device__ __forceinline__ void gemm_phase(PG8_LAS unsigned char* lds, const Gemm g, const Sched& S, const Epi& E, int wid_s_) {
;     ...
;         for (int t = 0; t < nt; t += 2) {
;             const bool last = (t == nt - 2);
;             const char* a1 = cA + (size_t)(t + 1) * kstep;
;             const char* a2 = last ? nA : cA + (size_t)(t + 2) * kstep; const char* b2 = last ? nB : cB + (size_t)(t + 2) * kstep;
;     ...
;             PG8_LDA(At, 1, 1); PG8_STAGE(PG8_SB(1, 0), b3, voffB); PG8_STAGE(PG8_SB(1, 1), b3 + hstep, voffB); PG8_STAGE(PG8_SA(1, 0), a3, voffA);
;             PG8_WAIT_V(8); PG8_WAIT_L(0); PG8_BAR; PG8_MMA(1, 0, At, B0); PG8_MMA(1, 1, At, B1); PG8_BAR; PG8_SCHED;
	s_add_i32 s20, s20, s50
	v_lshl_add_u64 v[150:151], v[150:151], 0, s[42:43]
	s_mov_b32 m0, s20
	ds_read_b128 v[180:183], v149 offset:49152
	ds_read_b128 v[196:199], v149 offset:50176
	ds_read_b128 v[200:203], v149 offset:51200
	ds_read_b128 v[204:207], v149 offset:52224
	ds_read_b128 v[208:211], v149 offset:53248
	ds_read_b128 v[212:215], v149 offset:54272
	ds_read_b128 v[216:219], v149 offset:55296
	ds_read_b128 v[220:223], v149 offset:56320
	global_load_lds_dwordx4 v[150:151], off
	v_lshl_add_u64 v[150:151], v[178:179], 0, s[42:43]
	s_add_i32 m0, s20, 0x2000
	s_add_i32 s20, s21, s50
	global_load_lds_dwordx4 v[150:151], off
	v_lshl_add_u64 v[150:151], v[188:189], 0, s[42:43]
	s_mov_b32 m0, s20
	s_nop 0
	global_load_lds_dwordx4 v[150:151], off
	v_lshl_add_u64 v[150:151], v[192:193], 0, s[42:43]
	s_add_i32 m0, s20, 0x2000
	s_nop 0
	global_load_lds_dwordx4 v[150:151], off
	v_lshl_add_u64 v[150:151], v[194:195], 0, s[42:43]
	s_mov_b32 m0, s89
	s_nop 0
	global_load_lds_dwordx4 v[150:151], off
	v_lshl_add_u64 v[150:151], v[224:225], 0, s[42:43]
	s_mov_b32 m0, s90
	s_nop 0
	global_load_lds_dwordx4 v[150:151], off
	s_waitcnt vmcnt(8)
	s_waitcnt lgkmcnt(0)
	s_barrier
	s_setprio 1
	s_waitcnt lgkmcnt(0)
	v_mfma_f32_16x16x32_bf16 v[92:95], v[122:125], v[180:183], v[92:95]
	v_mfma_f32_16x16x32_bf16 v[88:91], v[154:157], v[180:183], v[88:91]
	v_mfma_f32_16x16x32_bf16 v[84:87], v[122:125], v[200:203], v[84:87]
	v_mfma_f32_16x16x32_bf16 v[80:83], v[154:157], v[200:203], v[80:83]
	v_mfma_f32_16x16x32_bf16 v[76:79], v[122:125], v[208:211], v[76:79]
	v_mfma_f32_16x16x32_bf16 v[72:75], v[154:157], v[208:211], v[72:75]
	v_mfma_f32_16x16x32_bf16 v[68:71], v[122:125], v[216:219], v[68:71]
	v_mfma_f32_16x16x32_bf16 v[64:67], v[154:157], v[216:219], v[64:67]
	v_mfma_f32_16x16x32_bf16 v[92:95], v[126:129], v[196:199], v[92:95]
	v_mfma_f32_16x16x32_bf16 v[88:91], v[158:161], v[196:199], v[88:91]
	v_mfma_f32_16x16x32_bf16 v[84:87], v[126:129], v[204:207], v[84:87]
	v_mfma_f32_16x16x32_bf16 v[80:83], v[158:161], v[204:207], v[80:83]
	v_mfma_f32_16x16x32_bf16 v[76:79], v[126:129], v[212:215], v[76:79]
	v_mfma_f32_16x16x32_bf16 v[72:75], v[158:161], v[212:215], v[72:75]
	v_mfma_f32_16x16x32_bf16 v[68:71], v[126:129], v[220:223], v[68:71]
	v_mfma_f32_16x16x32_bf16 v[64:67], v[158:161], v[220:223], v[64:67]
	s_setprio 0
	s_setprio 1
	v_mfma_f32_16x16x32_bf16 v[28:31], v[162:165], v[180:183], v[28:31]
	v_mfma_f32_16x16x32_bf16 v[24:27], v[170:173], v[180:183], v[24:27]
	v_mfma_f32_16x16x32_bf16 v[20:23], v[162:165], v[200:203], v[20:23]
	v_mfma_f32_16x16x32_bf16 v[16:19], v[170:173], v[200:203], v[16:19]
	v_mfma_f32_16x16x32_bf16 v[12:15], v[162:165], v[208:211], v[12:15]
	v_mfma_f32_16x16x32_bf16 v[8:11], v[170:173], v[208:211], v[8:11]
	v_mfma_f32_16x16x32_bf16 v[4:7], v[162:165], v[216:219], v[4:7]
	v_mfma_f32_16x16x32_bf16 v[0:3], v[170:173], v[216:219], v[0:3]
	v_mfma_f32_16x16x32_bf16 v[28:31], v[166:169], v[196:199], v[28:31]
	v_mfma_f32_16x16x32_bf16 v[24:27], v[174:177], v[196:199], v[24:27]
	v_mfma_f32_16x16x32_bf16 v[20:23], v[166:169], v[204:207], v[20:23]
	v_mfma_f32_16x16x32_bf16 v[16:19], v[174:177], v[204:207], v[16:19]
	v_mfma_f32_16x16x32_bf16 v[12:15], v[166:169], v[212:215], v[12:15]
	v_mfma_f32_16x16x32_bf16 v[8:11], v[174:177], v[212:215], v[8:11]
	v_mfma_f32_16x16x32_bf16 v[4:7], v[166:169], v[220:223], v[4:7]
	v_mfma_f32_16x16x32_bf16 v[0:3], v[174:177], v[220:223], v[0:3]
	s_setprio 0
	s_barrier
	s_add_u32 vcc_lo, vcc_lo, 0x100
	s_addc_u32 vcc_hi, vcc_hi, 0
	s_add_u32 s2, s2, 0x100
	s_addc_u32 s3, s3, 0
	s_cmp_ge_i32 s84, s4
	s_mov_b32 s48, s84
	s_cbranch_scc0 .LBB0_628
	s_movk_i32 s21, 0x3fff
	v_add_u32_e32 v192, 64, v191

; #define PG8_STAGE(bufoff, gbase, voff) do { _Pragma("unroll") for (int _i = 0; _i < 2; ++_i) \
;         __builtin_amdgcn_global_load_lds((const unsigned*)((const char*)(gbase) + (voff)[_i]), (PG8_LAS unsigned*)(lds + (bufoff) + ldsw + _i * 8192), 16, 0, 0); } while (0)
; #define PG8_LDA(dst, b, h) do { _Pragma("unroll") for (int m = 0; m < 4; ++m) _Pragma("unroll") for (int k = 0; k < 2; ++k) dst[m][k] = *(const PG8_LAS bf16x8*)(lds + PG8_SA(b, h) + aoff + m * 2048 + k * 1024); } while (0)
; #define PG8_LDB(dst, b, h) do { _Pragma("unroll") for (int n = 0; n < 2; ++n) _Pragma("unroll") for (int k = 0; k < 2; ++k) dst[n][k] = *(const PG8_LAS bf16x8*)(lds + PG8_SB(b, h) + boff + n * 2048 + k * 1024); } while (0)
; #define PG8_MMA(ai, bj, At, Bt) do { __builtin_amdgcn_s_setprio(1); _Pragma("unroll") for (int m = 0; m < 4; ++m) _Pragma("unroll") for (int n = 0; n < 2; ++n) _Pragma("unroll") for (int k = 0; k < 2; ++k) \
;         acc[ai][bj][m][n] = __builtin_amdgcn_mfma_f32_16x16x32_bf16(Bt[n][k], At[m][k], acc[ai][bj][m][n], 0, 0, 0); __builtin_amdgcn_s_setprio(0); } while (0)
; #define PG8_WAIT_V(n) asm volatile("s_waitcnt vmcnt(" #n ")" ::: "memory")
; #define PG8_WAIT_L(n) asm volatile("s_waitcnt lgkmcnt(" #n ")" ::: "memory")
; template <class Epi, class Sched, bool ALIGN_EPI = false, bool SP2 = false>
; __device__ __forceinline__ void gemm_phase(PG8_LAS unsigned char* lds, const Gemm g, const Sched& S, const Epi& E, int wid_s_) {
;     ...
;             const bool last = (t == nt - 2);
;             const char* a1 = cA + (size_t)(t + 1) * kstep;
;             const char* a2 = last ? nA : cA + (size_t)(t + 2) * kstep; const char* b2 = last ? nB : cB + (size_t)(t + 2) * kstep;
;             const char* a3 = a2 + kstep; const char* b3 = b2 + kstep;
;             if (last && has_next) S.a_ready(nxt);
;             if constexpr (SP2) {
;             PG8_LDB(B0, 0, 0); PG8_LDB(B1, 0, 1); PG8_SCHED; PG8_LDA(At, 0, 0); PG8_STAGE(PG8_SA(1, 1), a1 + hstep, voffA);
;             PG8_WAIT_V(8); PG8_WAIT_L(0); PG8_BAR; PG8_MMA(0, 0, At, B0); PG8_MMA(0, 1, At, B1); PG8_BAR; PG8_SCHED;
;             PG8_LDA(At, 0, 1); PG8_STAGE(PG8_SB(0, 0), b2, voffB); PG8_STAGE(PG8_SB(0, 1), b2 + hstep, voffB); PG8_STAGE(PG8_SA(0, 0), a2, voffA);
;             PG8_WAIT_V(8); PG8_WAIT_L(0); PG8_BAR; PG8_MMA(1, 0, At, B0); PG8_MMA(1, 1, At, B1); PG8_BAR; PG8_SCHED;
.LBB0_788:
	s_add_i32 vcc_hi, s20, 2
	s_add_u32 s8, s18, 0x80
	s_addc_u32 s9, s19, 0
	s_add_i32 s78, 16, 0x10000
	s_cmp_eq_u32 s85, s20
	s_cselect_b32 s21, s3, s9
	s_cselect_b32 s20, s2, s8
	v_add_u32_e32 v96, s78, v147
	s_cselect_b32 s9, s17, vcc_lo
	s_cselect_b32 s8, s16, s91
	s_add_i32 s79, 16, 0x14000
	ds_read_b128 v[142:145], v96
	ds_read_b128 v[150:153], v96 offset:1024
	ds_read_b128 v[154:157], v96 offset:2048
	ds_read_b128 v[158:161], v96 offset:3072
	v_add_u32_e32 v96, s79, v147
	ds_read_b128 v[162:165], v96
	ds_read_b128 v[166:169], v96 offset:1024
	ds_read_b128 v[170:173], v96 offset:2048
	ds_read_b128 v[174:177], v96 offset:3072
	v_lshl_add_u64 v[178:179], s[18:19], 0, v[140:141]
	s_add_i32 m0, s48, 0xc000
	ds_read_b128 v[180:183], v149
	ds_read_b128 v[196:199], v149 offset:1024
	ds_read_b128 v[200:203], v149 offset:2048
	ds_read_b128 v[204:207], v149 offset:3072
	ds_read_b128 v[208:211], v149 offset:4096
	ds_read_b128 v[212:215], v149 offset:5120
	ds_read_b128 v[216:219], v149 offset:6144
	ds_read_b128 v[220:223], v149 offset:7168
	global_load_lds_dwordx4 v[178:179], off
	v_lshl_add_u64 v[178:179], s[18:19], 0, v[138:139]
	s_add_i32 m0, s48, 0xe000
	s_nop 0
	global_load_lds_dwordx4 v[178:179], off
	s_waitcnt vmcnt(8)
	s_waitcnt lgkmcnt(0)
	s_barrier
	s_setprio 1
	s_waitcnt lgkmcnt(0)
	v_mfma_f32_16x16x32_bf16 v[126:129], v[142:145], v[180:183], v[126:129]
	v_mfma_f32_16x16x32_bf16 v[122:125], v[154:157], v[180:183], v[122:125]
	v_mfma_f32_16x16x32_bf16 v[118:121], v[142:145], v[200:203], v[118:121]
	v_mfma_f32_16x16x32_bf16 v[114:117], v[154:157], v[200:203], v[114:117]
	v_mfma_f32_16x16x32_bf16 v[106:109], v[142:145], v[208:211], v[106:109]
	v_mfma_f32_16x16x32_bf16 v[98:101], v[154:157], v[208:211], v[98:101]
	v_mfma_f32_16x16x32_bf16 v[88:91], v[142:145], v[216:219], v[88:91]
	v_mfma_f32_16x16x32_bf16 v[80:83], v[154:157], v[216:219], v[80:83]
	v_mfma_f32_16x16x32_bf16 v[126:129], v[150:153], v[196:199], v[126:129]
	v_mfma_f32_16x16x32_bf16 v[122:125], v[158:161], v[196:199], v[122:125]
	v_mfma_f32_16x16x32_bf16 v[118:121], v[150:153], v[204:207], v[118:121]
	v_mfma_f32_16x16x32_bf16 v[114:117], v[158:161], v[204:207], v[114:117]
	v_mfma_f32_16x16x32_bf16 v[106:109], v[150:153], v[212:215], v[106:109]
	v_mfma_f32_16x16x32_bf16 v[98:101], v[158:161], v[212:215], v[98:101]
	v_mfma_f32_16x16x32_bf16 v[88:91], v[150:153], v[220:223], v[88:91]
	v_mfma_f32_16x16x32_bf16 v[80:83], v[158:161], v[220:223], v[80:83]
	s_setprio 0
	s_setprio 1
	v_mfma_f32_16x16x32_bf16 v[110:113], v[162:165], v[180:183], v[110:113]
	v_mfma_f32_16x16x32_bf16 v[102:105], v[170:173], v[180:183], v[102:105]
	v_mfma_f32_16x16x32_bf16 v[92:95], v[162:165], v[200:203], v[92:95]
	v_mfma_f32_16x16x32_bf16 v[84:87], v[170:173], v[200:203], v[84:87]
	v_mfma_f32_16x16x32_bf16 v[76:79], v[162:165], v[208:211], v[76:79]
	v_mfma_f32_16x16x32_bf16 v[72:75], v[170:173], v[208:211], v[72:75]
	v_mfma_f32_16x16x32_bf16 v[68:71], v[162:165], v[216:219], v[68:71]
	v_mfma_f32_16x16x32_bf16 v[64:67], v[170:173], v[216:219], v[64:67]
	v_mfma_f32_16x16x32_bf16 v[110:113], v[166:169], v[196:199], v[110:113]
	v_mfma_f32_16x16x32_bf16 v[102:105], v[174:177], v[196:199], v[102:105]
	v_mfma_f32_16x16x32_bf16 v[92:95], v[166:169], v[204:207], v[92:95]
	v_mfma_f32_16x16x32_bf16 v[84:87], v[174:177], v[204:207], v[84:87]
	v_mfma_f32_16x16x32_bf16 v[76:79], v[166:169], v[212:215], v[76:79]
	v_mfma_f32_16x16x32_bf16 v[72:75], v[174:177], v[212:215], v[72:75]
	v_mfma_f32_16x16x32_bf16 v[68:71], v[166:169], v[220:223], v[68:71]
	v_mfma_f32_16x16x32_bf16 v[64:67], v[174:177], v[220:223], v[64:67]
	s_setprio 0
	s_barrier
	s_add_i32 s78, s78, s41
	v_lshl_add_u64 v[178:179], s[8:9], 0, v[132:133]
	s_mov_b32 m0, s78
	ds_read_b128 v[180:183], v149 offset:16384
	ds_read_b128 v[196:199], v149 offset:17408
	ds_read_b128 v[200:203], v149 offset:18432
	ds_read_b128 v[204:207], v149 offset:19456
	ds_read_b128 v[208:211], v149 offset:20480
	ds_read_b128 v[212:215], v149 offset:21504
	ds_read_b128 v[216:219], v149 offset:22528
	ds_read_b128 v[220:223], v149 offset:23552
	global_load_lds_dwordx4 v[178:179], off
	s_add_i32 m0, s78, 0x2000
	v_lshl_add_u64 v[188:189], s[8:9], 0, v[136:137]
	s_add_u32 s8, s8, s4
	s_addc_u32 s9, s9, s5
	s_add_i32 s78, s79, s41
	global_load_lds_dwordx4 v[188:189], off
	v_lshl_add_u64 v[194:195], s[8:9], 0, v[132:133]
	s_mov_b32 m0, s78
	v_lshl_add_u64 v[224:225], s[8:9], 0, v[136:137]
	global_load_lds_dwordx4 v[194:195], off
	s_add_i32 m0, s78, 0x2000
	v_lshl_add_u64 v[226:227], s[20:21], 0, v[130:131]
	global_load_lds_dwordx4 v[224:225], off
	s_mov_b32 m0, s48
	v_lshl_add_u64 v[228:229], s[20:21], 0, v[134:135]
	global_load_lds_dwordx4 v[226:227], off
	s_mov_b32 m0, s49
	s_nop 0
	global_load_lds_dwordx4 v[228:229], off
	s_waitcnt vmcnt(8)
	s_waitcnt lgkmcnt(0)
	s_barrier
; #define PG8_STAGE(bufoff, gbase, voff) do { _Pragma("unroll") for (int _i = 0; _i < 2; ++_i) \
;         __builtin_amdgcn_global_load_lds((const unsigned*)((const char*)(gbase) + (voff)[_i]), (PG8_LAS unsigned*)(lds + (bufoff) + ldsw + _i * 8192), 16, 0, 0); } while (0)
; #define PG8_LDA(dst, b, h) do { _Pragma("unroll") for (int m = 0; m < 4; ++m) _Pragma("unroll") for (int k = 0; k < 2; ++k) dst[m][k] = *(const PG8_LAS bf16x8*)(lds + PG8_SA(b, h) + aoff + m * 2048 + k * 1024); } while (0)
; #define PG8_LDB(dst, b, h) do { _Pragma("unroll") for (int n = 0; n < 2; ++n) _Pragma("unroll") for (int k = 0; k < 2; ++k) dst[n][k] = *(const PG8_LAS bf16x8*)(lds + PG8_SB(b, h) + boff + n * 2048 + k * 1024); } while (0)
; #define PG8_MMA(ai, bj, At, Bt) do { __builtin_amdgcn_s_setprio(1); _Pragma("unroll") for (int m = 0; m < 4; ++m) _Pragma("unroll") for (int n = 0; n < 2; ++n) _Pragma("unroll") for (int k = 0; k < 2; ++k) \
;         acc[ai][bj][m][n] = __builtin_amdgcn_mfma_f32_16x16x32_bf16(Bt[n][k], At[m][k], acc[ai][bj][m][n], 0, 0, 0); __builtin_amdgcn_s_setprio(0); } while (0)
; #define PG8_WAIT_V(n) asm volatile("s_waitcnt vmcnt(" #n ")" ::: "memory")
; #define PG8_WAIT_L(n) asm volatile("s_waitcnt lgkmcnt(" #n ")" ::: "memory")
; #define PG8_BAR __builtin_amdgcn_s_barrier()
; #define PG8_SCHED __builtin_amdgcn_sched_barrier(0)
; template <class Epi, class Sched, bool ALIGN_EPI = false, bool SP2 = false>
; __device__ __forceinline__ void gemm_phase(PG8_LAS unsigned char* lds, const Gemm g, const Sched& S, const Epi& E, int wid_s_) {
;     ...
;             PG8_WAIT_V(8); PG8_WAIT_L(0); PG8_BAR; PG8_MMA(1, 0, At, B0); PG8_MMA(1, 1, At, B1); PG8_BAR; PG8_SCHED;
;             PG8_LDB(B0, 1, 0); PG8_LDB(B1, 1, 1); PG8_SCHED; PG8_LDA(At, 1, 0); PG8_STAGE(PG8_SA(0, 1), a2 + hstep, voffA);
;             PG8_WAIT_V(8); PG8_WAIT_L(0); PG8_BAR; PG8_MMA(0, 0, At, B0); PG8_MMA(0, 1, At, B1); PG8_BAR; PG8_SCHED;
	s_setprio 1
	s_waitcnt lgkmcnt(0)
	v_mfma_f32_16x16x32_bf16 v[60:63], v[142:145], v[180:183], v[60:63]
	v_mfma_f32_16x16x32_bf16 v[56:59], v[154:157], v[180:183], v[56:59]
	v_mfma_f32_16x16x32_bf16 v[52:55], v[142:145], v[200:203], v[52:55]
	v_mfma_f32_16x16x32_bf16 v[48:51], v[154:157], v[200:203], v[48:51]
	v_mfma_f32_16x16x32_bf16 v[40:43], v[142:145], v[208:211], v[40:43]
	v_mfma_f32_16x16x32_bf16 v[32:35], v[154:157], v[208:211], v[32:35]
	v_mfma_f32_16x16x32_bf16 v[24:27], v[142:145], v[216:219], v[24:27]
	v_mfma_f32_16x16x32_bf16 v[16:19], v[154:157], v[216:219], v[16:19]
	v_mfma_f32_16x16x32_bf16 v[60:63], v[150:153], v[196:199], v[60:63]
	v_mfma_f32_16x16x32_bf16 v[56:59], v[158:161], v[196:199], v[56:59]
	v_mfma_f32_16x16x32_bf16 v[52:55], v[150:153], v[204:207], v[52:55]
	v_mfma_f32_16x16x32_bf16 v[48:51], v[158:161], v[204:207], v[48:51]
	v_mfma_f32_16x16x32_bf16 v[40:43], v[150:153], v[212:215], v[40:43]
	v_mfma_f32_16x16x32_bf16 v[32:35], v[158:161], v[212:215], v[32:35]
	v_mfma_f32_16x16x32_bf16 v[24:27], v[150:153], v[220:223], v[24:27]
	v_mfma_f32_16x16x32_bf16 v[16:19], v[158:161], v[220:223], v[16:19]
	s_setprio 0
	s_setprio 1
	v_mfma_f32_16x16x32_bf16 v[44:47], v[162:165], v[180:183], v[44:47]
	v_mfma_f32_16x16x32_bf16 v[36:39], v[170:173], v[180:183], v[36:39]
	v_mfma_f32_16x16x32_bf16 v[28:31], v[162:165], v[200:203], v[28:31]
	v_mfma_f32_16x16x32_bf16 v[20:23], v[170:173], v[200:203], v[20:23]
	v_mfma_f32_16x16x32_bf16 v[12:15], v[162:165], v[208:211], v[12:15]
	v_mfma_f32_16x16x32_bf16 v[8:11], v[170:173], v[208:211], v[8:11]
	v_mfma_f32_16x16x32_bf16 v[4:7], v[162:165], v[216:219], v[4:7]
	v_mfma_f32_16x16x32_bf16 v[0:3], v[170:173], v[216:219], v[0:3]
	v_mfma_f32_16x16x32_bf16 v[44:47], v[166:169], v[196:199], v[44:47]
	v_mfma_f32_16x16x32_bf16 v[36:39], v[174:177], v[196:199], v[36:39]
	v_mfma_f32_16x16x32_bf16 v[28:31], v[166:169], v[204:207], v[28:31]
	v_mfma_f32_16x16x32_bf16 v[20:23], v[174:177], v[204:207], v[20:23]
	v_mfma_f32_16x16x32_bf16 v[12:15], v[166:169], v[212:215], v[12:15]
	v_mfma_f32_16x16x32_bf16 v[8:11], v[174:177], v[212:215], v[8:11]
	v_mfma_f32_16x16x32_bf16 v[4:7], v[166:169], v[220:223], v[4:7]
	v_mfma_f32_16x16x32_bf16 v[0:3], v[174:177], v[220:223], v[0:3]
	s_setprio 0
	s_barrier
	s_add_i32 s78, 16, 0x18000
	v_add_u32_e32 v96, s78, v147
	s_add_i32 s79, 16, 0x1c000
	ds_read_b128 v[142:145], v96
	ds_read_b128 v[150:153], v96 offset:1024
	ds_read_b128 v[154:157], v96 offset:2048
	ds_read_b128 v[158:161], v96 offset:3072
	v_add_u32_e32 v96, s79, v147
	ds_read_b128 v[162:165], v96
	ds_read_b128 v[166:169], v96 offset:1024
	ds_read_b128 v[170:173], v96 offset:2048
	ds_read_b128 v[174:177], v96 offset:3072
	s_add_u32 s8, s20, s4
	s_addc_u32 s9, s21, s5
	s_mov_b32 m0, s50
	v_lshl_add_u64 v[230:231], s[8:9], 0, v[130:131]
	ds_read_b128 v[180:183], v149 offset:32768
	ds_read_b128 v[196:199], v149 offset:33792
	ds_read_b128 v[200:203], v149 offset:34816
	ds_read_b128 v[204:207], v149 offset:35840
	ds_read_b128 v[208:211], v149 offset:36864
	ds_read_b128 v[212:215], v149 offset:37888
	ds_read_b128 v[216:219], v149 offset:38912
	ds_read_b128 v[220:223], v149 offset:39936
	global_load_lds_dwordx4 v[230:231], off
	v_lshl_add_u64 v[230:231], s[8:9], 0, v[134:135]
	s_mov_b32 m0, s51
	s_nop 0
	global_load_lds_dwordx4 v[230:231], off
	s_waitcnt vmcnt(8)
	s_waitcnt lgkmcnt(0)
	s_barrier
	s_setprio 1
	s_waitcnt lgkmcnt(0)
	v_mfma_f32_16x16x32_bf16 v[126:129], v[142:145], v[180:183], v[126:129]
	v_mfma_f32_16x16x32_bf16 v[122:125], v[154:157], v[180:183], v[122:125]
	v_mfma_f32_16x16x32_bf16 v[118:121], v[142:145], v[200:203], v[118:121]
	v_mfma_f32_16x16x32_bf16 v[114:117], v[154:157], v[200:203], v[114:117]
	v_mfma_f32_16x16x32_bf16 v[106:109], v[142:145], v[208:211], v[106:109]
	v_mfma_f32_16x16x32_bf16 v[98:101], v[154:157], v[208:211], v[98:101]
	v_mfma_f32_16x16x32_bf16 v[88:91], v[142:145], v[216:219], v[88:91]
	v_mfma_f32_16x16x32_bf16 v[80:83], v[154:157], v[216:219], v[80:83]
	v_mfma_f32_16x16x32_bf16 v[126:129], v[150:153], v[196:199], v[126:129]
	v_mfma_f32_16x16x32_bf16 v[122:125], v[158:161], v[196:199], v[122:125]
	v_mfma_f32_16x16x32_bf16 v[118:121], v[150:153], v[204:207], v[118:121]
	v_mfma_f32_16x16x32_bf16 v[114:117], v[158:161], v[204:207], v[114:117]
	v_mfma_f32_16x16x32_bf16 v[106:109], v[150:153], v[212:215], v[106:109]
	v_mfma_f32_16x16x32_bf16 v[98:101], v[158:161], v[212:215], v[98:101]
	v_mfma_f32_16x16x32_bf16 v[88:91], v[150:153], v[220:223], v[88:91]
	v_mfma_f32_16x16x32_bf16 v[80:83], v[158:161], v[220:223], v[80:83]
	s_setprio 0
	s_setprio 1
	v_mfma_f32_16x16x32_bf16 v[110:113], v[162:165], v[180:183], v[110:113]
	v_mfma_f32_16x16x32_bf16 v[102:105], v[170:173], v[180:183], v[102:105]
	v_mfma_f32_16x16x32_bf16 v[92:95], v[162:165], v[200:203], v[92:95]
	v_mfma_f32_16x16x32_bf16 v[84:87], v[170:173], v[200:203], v[84:87]
	v_mfma_f32_16x16x32_bf16 v[76:79], v[162:165], v[208:211], v[76:79]
	v_mfma_f32_16x16x32_bf16 v[72:75], v[170:173], v[208:211], v[72:75]
	v_mfma_f32_16x16x32_bf16 v[68:71], v[162:165], v[216:219], v[68:71]
	v_mfma_f32_16x16x32_bf16 v[64:67], v[170:173], v[216:219], v[64:67]
	v_mfma_f32_16x16x32_bf16 v[110:113], v[166:169], v[196:199], v[110:113]
	v_mfma_f32_16x16x32_bf16 v[102:105], v[174:177], v[196:199], v[102:105]
	v_mfma_f32_16x16x32_bf16 v[92:95], v[166:169], v[204:207], v[92:95]
	v_mfma_f32_16x16x32_bf16 v[84:87], v[174:177], v[204:207], v[84:87]
	v_mfma_f32_16x16x32_bf16 v[76:79], v[166:169], v[212:215], v[76:79]
	v_mfma_f32_16x16x32_bf16 v[72:75], v[174:177], v[212:215], v[72:75]
	v_mfma_f32_16x16x32_bf16 v[68:71], v[166:169], v[220:223], v[68:71]
	v_mfma_f32_16x16x32_bf16 v[64:67], v[174:177], v[220:223], v[64:67]
	s_setprio 0
	s_barrier
; #define PG8_STAGE(bufoff, gbase, voff) do { _Pragma("unroll") for (int _i = 0; _i < 2; ++_i) \
;         __builtin_amdgcn_global_load_lds((const unsigned*)((const char*)(gbase) + (voff)[_i]), (PG8_LAS unsigned*)(lds + (bufoff) + ldsw + _i * 8192), 16, 0, 0); } while (0)
; #define PG8_LDA(dst, b, h) do { _Pragma("unroll") for (int m = 0; m < 4; ++m) _Pragma("unroll") for (int k = 0; k < 2; ++k) dst[m][k] = *(const PG8_LAS bf16x8*)(lds + PG8_SA(b, h) + aoff + m * 2048 + k * 1024); } while (0)
; #define PG8_MMA(ai, bj, At, Bt) do { __builtin_amdgcn_s_setprio(1); _Pragma("unroll") for (int m = 0; m < 4; ++m) _Pragma("unroll") for (int n = 0; n < 2; ++n) _Pragma("unroll") for (int k = 0; k < 2; ++k) \
;         acc[ai][bj][m][n] = __builtin_amdgcn_mfma_f32_16x16x32_bf16(Bt[n][k], At[m][k], acc[ai][bj][m][n], 0, 0, 0); __builtin_amdgcn_s_setprio(0); } while (0)
; #define PG8_WAIT_V(n) asm volatile("s_waitcnt vmcnt(" #n ")" ::: "memory")
; #define PG8_WAIT_L(n) asm volatile("s_waitcnt lgkmcnt(" #n ")" ::: "memory")
; #define PG8_BAR __builtin_amdgcn_s_barrier()
; #define PG8_SCHED __builtin_amdgcn_sched_barrier(0)
; template <class Epi, class Sched, bool ALIGN_EPI = false, bool SP2 = false>
; __device__ __forceinline__ void gemm_phase(PG8_LAS unsigned char* lds, const Gemm g, const Sched& S, const Epi& E, int wid_s_) {
;     ...
;         for (int t = 0; t < nt; t += 2) {
;             const bool last = (t == nt - 2);
;             const char* a1 = cA + (size_t)(t + 1) * kstep;
;             const char* a2 = last ? nA : cA + (size_t)(t + 2) * kstep; const char* b2 = last ? nB : cB + (size_t)(t + 2) * kstep;
;     ...
;             PG8_LDA(At, 1, 1); PG8_STAGE(PG8_SB(1, 0), b3, voffB); PG8_STAGE(PG8_SB(1, 1), b3 + hstep, voffB); PG8_STAGE(PG8_SA(1, 0), a3, voffA);
;             PG8_WAIT_V(8); PG8_WAIT_L(0); PG8_BAR; PG8_MMA(1, 0, At, B0); PG8_MMA(1, 1, At, B1); PG8_BAR; PG8_SCHED;
	s_add_i32 s8, s78, s41
	v_lshl_add_u64 v[178:179], v[178:179], 0, s[42:43]
	s_mov_b32 m0, s8
	ds_read_b128 v[180:183], v149 offset:49152
	ds_read_b128 v[196:199], v149 offset:50176
	ds_read_b128 v[200:203], v149 offset:51200
	ds_read_b128 v[204:207], v149 offset:52224
	ds_read_b128 v[208:211], v149 offset:53248
	ds_read_b128 v[212:215], v149 offset:54272
	ds_read_b128 v[216:219], v149 offset:55296
	ds_read_b128 v[220:223], v149 offset:56320
	global_load_lds_dwordx4 v[178:179], off
	v_lshl_add_u64 v[178:179], v[188:189], 0, s[42:43]
	s_add_i32 m0, s8, 0x2000
	s_add_i32 s8, s79, s41
	global_load_lds_dwordx4 v[178:179], off
	v_lshl_add_u64 v[178:179], v[194:195], 0, s[42:43]
	s_mov_b32 m0, s8
	s_nop 0
	global_load_lds_dwordx4 v[178:179], off
	v_lshl_add_u64 v[178:179], v[224:225], 0, s[42:43]
	s_add_i32 m0, s8, 0x2000
	s_nop 0
	global_load_lds_dwordx4 v[178:179], off
	v_lshl_add_u64 v[178:179], v[226:227], 0, s[42:43]
	s_mov_b32 m0, s80
	s_nop 0
	global_load_lds_dwordx4 v[178:179], off
	v_lshl_add_u64 v[178:179], v[228:229], 0, s[42:43]
	s_mov_b32 m0, s81
	s_nop 0
	global_load_lds_dwordx4 v[178:179], off
	s_waitcnt vmcnt(8)
	s_waitcnt lgkmcnt(0)
	s_barrier
	s_setprio 1
	s_waitcnt lgkmcnt(0)
	v_mfma_f32_16x16x32_bf16 v[60:63], v[142:145], v[180:183], v[60:63]
	v_mfma_f32_16x16x32_bf16 v[56:59], v[154:157], v[180:183], v[56:59]
	v_mfma_f32_16x16x32_bf16 v[52:55], v[142:145], v[200:203], v[52:55]
	v_mfma_f32_16x16x32_bf16 v[48:51], v[154:157], v[200:203], v[48:51]
	v_mfma_f32_16x16x32_bf16 v[40:43], v[142:145], v[208:211], v[40:43]
	v_mfma_f32_16x16x32_bf16 v[32:35], v[154:157], v[208:211], v[32:35]
	v_mfma_f32_16x16x32_bf16 v[24:27], v[142:145], v[216:219], v[24:27]
	v_mfma_f32_16x16x32_bf16 v[16:19], v[154:157], v[216:219], v[16:19]
	v_mfma_f32_16x16x32_bf16 v[60:63], v[150:153], v[196:199], v[60:63]
	v_mfma_f32_16x16x32_bf16 v[56:59], v[158:161], v[196:199], v[56:59]
	v_mfma_f32_16x16x32_bf16 v[52:55], v[150:153], v[204:207], v[52:55]
	v_mfma_f32_16x16x32_bf16 v[48:51], v[158:161], v[204:207], v[48:51]
	v_mfma_f32_16x16x32_bf16 v[40:43], v[150:153], v[212:215], v[40:43]
	v_mfma_f32_16x16x32_bf16 v[32:35], v[158:161], v[212:215], v[32:35]
	v_mfma_f32_16x16x32_bf16 v[24:27], v[150:153], v[220:223], v[24:27]
	v_mfma_f32_16x16x32_bf16 v[16:19], v[158:161], v[220:223], v[16:19]
	s_setprio 0
	s_setprio 1
	v_mfma_f32_16x16x32_bf16 v[44:47], v[162:165], v[180:183], v[44:47]
	v_mfma_f32_16x16x32_bf16 v[36:39], v[170:173], v[180:183], v[36:39]
	v_mfma_f32_16x16x32_bf16 v[28:31], v[162:165], v[200:203], v[28:31]
	v_mfma_f32_16x16x32_bf16 v[20:23], v[170:173], v[200:203], v[20:23]
	v_mfma_f32_16x16x32_bf16 v[12:15], v[162:165], v[208:211], v[12:15]
	v_mfma_f32_16x16x32_bf16 v[8:11], v[170:173], v[208:211], v[8:11]
	v_mfma_f32_16x16x32_bf16 v[4:7], v[162:165], v[216:219], v[4:7]
	v_mfma_f32_16x16x32_bf16 v[0:3], v[170:173], v[216:219], v[0:3]
	v_mfma_f32_16x16x32_bf16 v[44:47], v[166:169], v[196:199], v[44:47]
	v_mfma_f32_16x16x32_bf16 v[36:39], v[174:177], v[196:199], v[36:39]
	v_mfma_f32_16x16x32_bf16 v[28:31], v[166:169], v[204:207], v[28:31]
	v_mfma_f32_16x16x32_bf16 v[20:23], v[174:177], v[204:207], v[20:23]
	v_mfma_f32_16x16x32_bf16 v[12:15], v[166:169], v[212:215], v[12:15]
	v_mfma_f32_16x16x32_bf16 v[8:11], v[174:177], v[212:215], v[8:11]
	v_mfma_f32_16x16x32_bf16 v[4:7], v[166:169], v[220:223], v[4:7]
	v_mfma_f32_16x16x32_bf16 v[0:3], v[174:177], v[220:223], v[0:3]
	s_setprio 0
	s_barrier
	s_add_u32 s91, s91, 0x100
	s_addc_u32 vcc_lo, vcc_lo, 0
	s_add_u32 s18, s18, 0x100
	s_addc_u32 s19, s19, 0
	s_cmp_ge_i32 vcc_hi, s82
	s_mov_b32 s20, vcc_hi
	s_cbranch_scc0 .LBB0_788
; __device__ __forceinline__ unsigned cvtpk(float lo, float hi) { f32x2_t v = {lo, hi}; bf16x2_t b = __builtin_convertvector(v, bf16x2_t); return __builtin_bit_cast(unsigned, b); }
;     __device__ __forceinline__ void operator()(const f32x4 (&acc)[2][2][4][2], const Unit& u, int wr, int wc, int fr, int fq) const {
;     ...
;                     const f32x4 v0 = acc[ai][bj][m][0] * scale, v1 = acc[ai][bj][m][1] * scale;
;                     u32x4 w; w.x = cvtpk(v0[0], v0[1]); w.y = cvtpk(v0[2], v0[3]); w.z = cvtpk(v1[0], v1[1]); w.w = cvtpk(v1[2], v1[3]);
	s_mov_b32 s8, 0x39b504f3
	v_pk_mul_f32 v[128:129], v[128:129], s[8:9] op_sel_hi:[1,0]
	v_pk_mul_f32 v[126:127], v[126:127], s[8:9] op_sel_hi:[1,0]
	v_pk_mul_f32 v[124:125], v[124:125], s[8:9] op_sel_hi:[1,0]
	v_pk_mul_f32 v[122:123], v[122:123], s[8:9] op_sel_hi:[1,0]
	v_pk_mul_f32 v[142:143], v[112:113], s[8:9] op_sel_hi:[1,0]
	v_pk_mul_f32 v[144:145], v[110:111], s[8:9] op_sel_hi:[1,0]
	v_pk_mul_f32 v[152:153], v[104:105], s[8:9] op_sel_hi:[1,0]
	v_pk_mul_f32 v[154:155], v[102:103], s[8:9] op_sel_hi:[1,0]
	v_pk_mul_f32 v[102:103], v[120:121], s[8:9] op_sel_hi:[1,0]
	v_pk_mul_f32 v[104:105], v[118:119], s[8:9] op_sel_hi:[1,0]
	v_pk_mul_f32 v[110:111], v[116:117], s[8:9] op_sel_hi:[1,0]
	v_pk_mul_f32 v[112:113], v[114:115], s[8:9] op_sel_hi:[1,0]
	v_pk_mul_f32 v[114:115], v[94:95], s[8:9] op_sel_hi:[1,0]
	v_pk_mul_f32 v[116:117], v[92:93], s[8:9] op_sel_hi:[1,0]
	v_pk_mul_f32 v[118:119], v[86:87], s[8:9] op_sel_hi:[1,0]
	v_pk_mul_f32 v[120:121], v[84:85], s[8:9] op_sel_hi:[1,0]
	v_pk_mul_f32 v[84:85], v[108:109], s[8:9] op_sel_hi:[1,0]
	v_pk_mul_f32 v[86:87], v[106:107], s[8:9] op_sel_hi:[1,0]
	v_pk_mul_f32 v[92:93], v[100:101], s[8:9] op_sel_hi:[1,0]
	v_pk_mul_f32 v[94:95], v[98:99], s[8:9] op_sel_hi:[1,0]
	v_pk_mul_f32 v[98:99], v[78:79], s[8:9] op_sel_hi:[1,0]
	v_pk_mul_f32 v[100:101], v[76:77], s[8:9] op_sel_hi:[1,0]
	v_pk_mul_f32 v[106:107], v[74:75], s[8:9] op_sel_hi:[1,0]
	v_pk_mul_f32 v[108:109], v[72:73], s[8:9] op_sel_hi:[1,0]
	v_pk_mul_f32 v[72:73], v[90:91], s[8:9] op_sel_hi:[1,0]
	v_pk_mul_f32 v[74:75], v[88:89], s[8:9] op_sel_hi:[1,0]
	v_pk_mul_f32 v[76:77], v[82:83], s[8:9] op_sel_hi:[1,0]
	v_pk_mul_f32 v[78:79], v[80:81], s[8:9] op_sel_hi:[1,0]
	v_pk_mul_f32 v[70:71], v[70:71], s[8:9] op_sel_hi:[1,0]
	v_pk_mul_f32 v[68:69], v[68:69], s[8:9] op_sel_hi:[1,0]
	v_pk_mul_f32 v[66:67], v[66:67], s[8:9] op_sel_hi:[1,0]
	v_pk_mul_f32 v[64:65], v[64:65], s[8:9] op_sel_hi:[1,0]
	v_pk_mul_f32 v[62:63], v[62:63], s[8:9] op_sel_hi:[1,0]
	v_pk_mul_f32 v[60:61], v[60:61], s[8:9] op_sel_hi:[1,0]
	v_pk_mul_f32 v[58:59], v[58:59], s[8:9] op_sel_hi:[1,0]
	v_pk_mul_f32 v[56:57], v[56:57], s[8:9] op_sel_hi:[1,0]
	v_pk_mul_f32 v[80:81], v[46:47], s[8:9] op_sel_hi:[1,0]
	v_pk_mul_f32 v[82:83], v[44:45], s[8:9] op_sel_hi:[1,0]
	v_pk_mul_f32 v[88:89], v[38:39], s[8:9] op_sel_hi:[1,0]
	v_pk_mul_f32 v[90:91], v[36:37], s[8:9] op_sel_hi:[1,0]
	v_pk_mul_f32 v[36:37], v[54:55], s[8:9] op_sel_hi:[1,0]
	v_pk_mul_f32 v[38:39], v[52:53], s[8:9] op_sel_hi:[1,0]
	v_pk_mul_f32 v[44:45], v[50:51], s[8:9] op_sel_hi:[1,0]
	v_pk_mul_f32 v[46:47], v[48:49], s[8:9] op_sel_hi:[1,0]
	v_pk_mul_f32 v[48:49], v[30:31], s[8:9] op_sel_hi:[1,0]
	v_pk_mul_f32 v[50:51], v[28:29], s[8:9] op_sel_hi:[1,0]
	v_pk_mul_f32 v[52:53], v[22:23], s[8:9] op_sel_hi:[1,0]
	v_pk_mul_f32 v[54:55], v[20:21], s[8:9] op_sel_hi:[1,0]
	v_pk_mul_f32 v[20:21], v[42:43], s[8:9] op_sel_hi:[1,0]
	v_pk_mul_f32 v[22:23], v[40:41], s[8:9] op_sel_hi:[1,0]
	v_pk_mul_f32 v[28:29], v[34:35], s[8:9] op_sel_hi:[1,0]
	v_pk_mul_f32 v[30:31], v[32:33], s[8:9] op_sel_hi:[1,0]
	v_pk_mul_f32 v[32:33], v[14:15], s[8:9] op_sel_hi:[1,0]
	v_pk_mul_f32 v[34:35], v[12:13], s[8:9] op_sel_hi:[1,0]
	v_pk_mul_f32 v[40:41], v[10:11], s[8:9] op_sel_hi:[1,0]
	v_pk_mul_f32 v[42:43], v[8:9], s[8:9] op_sel_hi:[1,0]
	v_pk_mul_f32 v[8:9], v[26:27], s[8:9] op_sel_hi:[1,0]
	v_pk_mul_f32 v[10:11], v[24:25], s[8:9] op_sel_hi:[1,0]
	v_pk_mul_f32 v[12:13], v[18:19], s[8:9] op_sel_hi:[1,0]
	v_pk_mul_f32 v[14:15], v[16:17], s[8:9] op_sel_hi:[1,0]
	v_pk_mul_f32 v[6:7], v[6:7], s[8:9] op_sel_hi:[1,0]
	v_pk_mul_f32 v[4:5], v[4:5], s[8:9] op_sel_hi:[1,0]
	v_pk_mul_f32 v[2:3], v[2:3], s[8:9] op_sel_hi:[1,0]
	v_pk_mul_f32 v[0:1], v[0:1], s[8:9] op_sel_hi:[1,0]

; #define PG8_STAGE(bufoff, gbase, voff) do { _Pragma("unroll") for (int _i = 0; _i < 2; ++_i) \
;         __builtin_amdgcn_global_load_lds((const unsigned*)((const char*)(gbase) + (voff)[_i]), (PG8_LAS unsigned*)(lds + (bufoff) + ldsw + _i * 8192), 16, 0, 0); } while (0)
; #define PG8_LDA(dst, b, h) do { _Pragma("unroll") for (int m = 0; m < 4; ++m) _Pragma("unroll") for (int k = 0; k < 2; ++k) dst[m][k] = *(const PG8_LAS bf16x8*)(lds + PG8_SA(b, h) + aoff + m * 2048 + k * 1024); } while (0)
; #define PG8_LDB(dst, b, h) do { _Pragma("unroll") for (int n = 0; n < 2; ++n) _Pragma("unroll") for (int k = 0; k < 2; ++k) dst[n][k] = *(const PG8_LAS bf16x8*)(lds + PG8_SB(b, h) + boff + n * 2048 + k * 1024); } while (0)
; #define PG8_MMA(ai, bj, At, Bt) do { __builtin_amdgcn_s_setprio(1); _Pragma("unroll") for (int m = 0; m < 4; ++m) _Pragma("unroll") for (int n = 0; n < 2; ++n) _Pragma("unroll") for (int k = 0; k < 2; ++k) \
;         acc[ai][bj][m][n] = __builtin_amdgcn_mfma_f32_16x16x32_bf16(Bt[n][k], At[m][k], acc[ai][bj][m][n], 0, 0, 0); __builtin_amdgcn_s_setprio(0); } while (0)
; #define PG8_WAIT_V(n) asm volatile("s_waitcnt vmcnt(" #n ")" ::: "memory")
; #define PG8_WAIT_L(n) asm volatile("s_waitcnt lgkmcnt(" #n ")" ::: "memory")
; template <class Epi, class Sched, bool ALIGN_EPI = false, bool SP2 = false>
; __device__ __forceinline__ void gemm_phase(PG8_LAS unsigned char* lds, const Gemm g, const Sched& S, const Epi& E, int wid_s_) {
;     ...
;             const bool last = (t == nt - 2);
;             const char* a1 = cA + (size_t)(t + 1) * kstep;
;             const char* a2 = last ? nA : cA + (size_t)(t + 2) * kstep; const char* b2 = last ? nB : cB + (size_t)(t + 2) * kstep;
;             const char* a3 = a2 + kstep; const char* b3 = b2 + kstep;
;             if (last && has_next) S.a_ready(nxt);
;             if constexpr (SP2) {
;             PG8_LDB(B0, 0, 0); PG8_LDB(B1, 0, 1); PG8_SCHED; PG8_LDA(At, 0, 0); PG8_STAGE(PG8_SA(1, 1), a1 + hstep, voffA);
;             PG8_WAIT_V(8); PG8_WAIT_L(0); PG8_BAR; PG8_MMA(0, 0, At, B0); PG8_MMA(0, 1, At, B1); PG8_BAR; PG8_SCHED;
;             PG8_LDA(At, 0, 1); PG8_STAGE(PG8_SB(0, 0), b2, voffB); PG8_STAGE(PG8_SB(0, 1), b2 + hstep, voffB); PG8_STAGE(PG8_SA(0, 0), a2, voffA);
;             PG8_WAIT_V(8); PG8_WAIT_L(0); PG8_BAR; PG8_MMA(1, 0, At, B0); PG8_MMA(1, 1, At, B1); PG8_BAR; PG8_SCHED;
.LBB0_886:
	s_add_i32 s91, s18, 2
	s_add_u32 s8, s2, 0x80
	s_addc_u32 s19, s3, 0
	s_add_i32 s25, 16, 0x10000
	s_cmp_eq_u32 s88, s18
	s_cselect_b32 s19, s15, s19
	s_cselect_b32 s18, s14, s8
	v_add_u32_e32 v96, s25, v147
	s_cselect_b32 s79, s17, vcc_hi
	s_cselect_b32 s78, s16, vcc_lo
	s_add_i32 s8, 16, 0x14000
	ds_read_b128 v[132:135], v96
	ds_read_b128 v[136:139], v96 offset:1024
	ds_read_b128 v[160:163], v96 offset:2048
	ds_read_b128 v[164:167], v96 offset:3072
	v_add_u32_e32 v96, s8, v147
	ds_read_b128 v[168:171], v96
	ds_read_b128 v[172:175], v96 offset:1024
	ds_read_b128 v[176:179], v96 offset:2048
	ds_read_b128 v[180:183], v96 offset:3072
	v_lshl_add_u64 v[98:99], s[2:3], 0, v[156:157]
	s_add_i32 m0, s41, 0xc000
	ds_read_b128 v[194:197], v150
	ds_read_b128 v[198:201], v150 offset:1024
	ds_read_b128 v[202:205], v150 offset:2048
	ds_read_b128 v[206:209], v150 offset:3072
	ds_read_b128 v[210:213], v150 offset:4096
	ds_read_b128 v[214:217], v150 offset:5120
	ds_read_b128 v[218:221], v150 offset:6144
	ds_read_b128 v[222:225], v150 offset:7168
	global_load_lds_dwordx4 v[98:99], off
	v_lshl_add_u64 v[98:99], s[2:3], 0, v[154:155]
	s_add_i32 m0, s41, 0xe000
	s_nop 0
	global_load_lds_dwordx4 v[98:99], off
	s_waitcnt vmcnt(8)
	s_waitcnt lgkmcnt(0)
	s_barrier
	s_setprio 1
	s_waitcnt lgkmcnt(0)
	v_mfma_f32_16x16x32_bf16 v[128:131], v[132:135], v[194:197], v[128:131]
	v_mfma_f32_16x16x32_bf16 v[124:127], v[160:163], v[194:197], v[124:127]
	v_mfma_f32_16x16x32_bf16 v[120:123], v[132:135], v[202:205], v[120:123]
	v_mfma_f32_16x16x32_bf16 v[112:115], v[160:163], v[202:205], v[112:115]
	v_mfma_f32_16x16x32_bf16 v[104:107], v[132:135], v[210:213], v[104:107]
	v_mfma_f32_16x16x32_bf16 v[92:95], v[160:163], v[210:213], v[92:95]
	v_mfma_f32_16x16x32_bf16 v[84:87], v[132:135], v[218:221], v[84:87]
	v_mfma_f32_16x16x32_bf16 v[76:79], v[160:163], v[218:221], v[76:79]
	v_mfma_f32_16x16x32_bf16 v[128:131], v[136:139], v[198:201], v[128:131]
	v_mfma_f32_16x16x32_bf16 v[124:127], v[164:167], v[198:201], v[124:127]
	v_mfma_f32_16x16x32_bf16 v[120:123], v[136:139], v[206:209], v[120:123]
	v_mfma_f32_16x16x32_bf16 v[112:115], v[164:167], v[206:209], v[112:115]
	v_mfma_f32_16x16x32_bf16 v[104:107], v[136:139], v[214:217], v[104:107]
	v_mfma_f32_16x16x32_bf16 v[92:95], v[164:167], v[214:217], v[92:95]
	v_mfma_f32_16x16x32_bf16 v[84:87], v[136:139], v[222:225], v[84:87]
	v_mfma_f32_16x16x32_bf16 v[76:79], v[164:167], v[222:225], v[76:79]
	s_setprio 0
	s_setprio 1
	v_mfma_f32_16x16x32_bf16 v[116:119], v[168:171], v[194:197], v[116:119]
	v_mfma_f32_16x16x32_bf16 v[108:111], v[176:179], v[194:197], v[108:111]
	v_mfma_f32_16x16x32_bf16 v[98:101], v[168:171], v[202:205], v[100:103]
	v_mfma_f32_16x16x32_bf16 v[88:91], v[176:179], v[202:205], v[88:91]
	v_mfma_f32_16x16x32_bf16 v[80:83], v[168:171], v[210:213], v[80:83]
	v_mfma_f32_16x16x32_bf16 v[72:75], v[176:179], v[210:213], v[72:75]
	v_mfma_f32_16x16x32_bf16 v[68:71], v[168:171], v[218:221], v[68:71]
	v_mfma_f32_16x16x32_bf16 v[64:67], v[176:179], v[218:221], v[64:67]
	v_mfma_f32_16x16x32_bf16 v[116:119], v[172:175], v[198:201], v[116:119]
	v_mfma_f32_16x16x32_bf16 v[108:111], v[180:183], v[198:201], v[108:111]
	v_mfma_f32_16x16x32_bf16 v[98:101], v[172:175], v[206:209], v[98:101]
	v_mfma_f32_16x16x32_bf16 v[88:91], v[180:183], v[206:209], v[88:91]
	v_mfma_f32_16x16x32_bf16 v[80:83], v[172:175], v[214:217], v[80:83]
	v_mfma_f32_16x16x32_bf16 v[72:75], v[180:183], v[214:217], v[72:75]
	v_mfma_f32_16x16x32_bf16 v[68:71], v[172:175], v[222:225], v[68:71]
	v_mfma_f32_16x16x32_bf16 v[64:67], v[180:183], v[222:225], v[64:67]
	s_setprio 0
	s_barrier
	s_add_i32 s25, s25, s40
	v_lshl_add_u64 v[158:159], s[78:79], 0, v[142:143]
	s_mov_b32 m0, s25
	ds_read_b128 v[194:197], v150 offset:16384
	ds_read_b128 v[198:201], v150 offset:17408
	ds_read_b128 v[202:205], v150 offset:18432
	ds_read_b128 v[206:209], v150 offset:19456
	ds_read_b128 v[210:213], v150 offset:20480
	ds_read_b128 v[214:217], v150 offset:21504
	ds_read_b128 v[218:221], v150 offset:22528
	ds_read_b128 v[222:225], v150 offset:23552
	global_load_lds_dwordx4 v[158:159], off
	s_add_i32 m0, s25, 0x2000
	v_lshl_add_u64 v[188:189], s[78:79], 0, v[152:153]
	s_add_u32 s78, s78, s4
	s_addc_u32 s79, s79, s5
	s_add_i32 s8, s8, s40
	global_load_lds_dwordx4 v[188:189], off
	v_lshl_add_u64 v[226:227], s[78:79], 0, v[142:143]
	s_mov_b32 m0, s8
	v_lshl_add_u64 v[228:229], s[78:79], 0, v[152:153]
	global_load_lds_dwordx4 v[226:227], off
	s_add_i32 m0, s8, 0x2000
	v_lshl_add_u64 v[230:231], s[18:19], 0, v[140:141]
	global_load_lds_dwordx4 v[228:229], off
	s_mov_b32 m0, s41
	v_lshl_add_u64 v[232:233], s[18:19], 0, v[144:145]
	global_load_lds_dwordx4 v[230:231], off
	s_mov_b32 m0, s48
	s_nop 0
	global_load_lds_dwordx4 v[232:233], off
	s_waitcnt vmcnt(8)
	s_waitcnt lgkmcnt(0)
	s_barrier
; #define PG8_STAGE(bufoff, gbase, voff) do { _Pragma("unroll") for (int _i = 0; _i < 2; ++_i) \
;         __builtin_amdgcn_global_load_lds((const unsigned*)((const char*)(gbase) + (voff)[_i]), (PG8_LAS unsigned*)(lds + (bufoff) + ldsw + _i * 8192), 16, 0, 0); } while (0)
; #define PG8_LDA(dst, b, h) do { _Pragma("unroll") for (int m = 0; m < 4; ++m) _Pragma("unroll") for (int k = 0; k < 2; ++k) dst[m][k] = *(const PG8_LAS bf16x8*)(lds + PG8_SA(b, h) + aoff + m * 2048 + k * 1024); } while (0)
; #define PG8_LDB(dst, b, h) do { _Pragma("unroll") for (int n = 0; n < 2; ++n) _Pragma("unroll") for (int k = 0; k < 2; ++k) dst[n][k] = *(const PG8_LAS bf16x8*)(lds + PG8_SB(b, h) + boff + n * 2048 + k * 1024); } while (0)
; #define PG8_MMA(ai, bj, At, Bt) do { __builtin_amdgcn_s_setprio(1); _Pragma("unroll") for (int m = 0; m < 4; ++m) _Pragma("unroll") for (int n = 0; n < 2; ++n) _Pragma("unroll") for (int k = 0; k < 2; ++k) \
;         acc[ai][bj][m][n] = __builtin_amdgcn_mfma_f32_16x16x32_bf16(Bt[n][k], At[m][k], acc[ai][bj][m][n], 0, 0, 0); __builtin_amdgcn_s_setprio(0); } while (0)
; #define PG8_WAIT_V(n) asm volatile("s_waitcnt vmcnt(" #n ")" ::: "memory")
; #define PG8_WAIT_L(n) asm volatile("s_waitcnt lgkmcnt(" #n ")" ::: "memory")
; #define PG8_BAR __builtin_amdgcn_s_barrier()
; #define PG8_SCHED __builtin_amdgcn_sched_barrier(0)
; template <class Epi, class Sched, bool ALIGN_EPI = false, bool SP2 = false>
; __device__ __forceinline__ void gemm_phase(PG8_LAS unsigned char* lds, const Gemm g, const Sched& S, const Epi& E, int wid_s_) {
;     ...
;             PG8_WAIT_V(8); PG8_WAIT_L(0); PG8_BAR; PG8_MMA(1, 0, At, B0); PG8_MMA(1, 1, At, B1); PG8_BAR; PG8_SCHED;
;             PG8_LDB(B0, 1, 0); PG8_LDB(B1, 1, 1); PG8_SCHED; PG8_LDA(At, 1, 0); PG8_STAGE(PG8_SA(0, 1), a2 + hstep, voffA);
;             PG8_WAIT_V(8); PG8_WAIT_L(0); PG8_BAR; PG8_MMA(0, 0, At, B0); PG8_MMA(0, 1, At, B1); PG8_BAR; PG8_SCHED;
	s_setprio 1
	s_waitcnt lgkmcnt(0)
	v_mfma_f32_16x16x32_bf16 v[60:63], v[132:135], v[194:197], v[60:63]
	v_mfma_f32_16x16x32_bf16 v[56:59], v[160:163], v[194:197], v[56:59]
	v_mfma_f32_16x16x32_bf16 v[52:55], v[132:135], v[202:205], v[52:55]
	v_mfma_f32_16x16x32_bf16 v[48:51], v[160:163], v[202:205], v[48:51]
	v_mfma_f32_16x16x32_bf16 v[36:39], v[132:135], v[210:213], v[36:39]
	v_mfma_f32_16x16x32_bf16 v[32:35], v[160:163], v[210:213], v[32:35]
	v_mfma_f32_16x16x32_bf16 v[20:23], v[132:135], v[218:221], v[20:23]
	v_mfma_f32_16x16x32_bf16 v[16:19], v[160:163], v[218:221], v[16:19]
	v_mfma_f32_16x16x32_bf16 v[60:63], v[136:139], v[198:201], v[60:63]
	v_mfma_f32_16x16x32_bf16 v[56:59], v[164:167], v[198:201], v[56:59]
	v_mfma_f32_16x16x32_bf16 v[52:55], v[136:139], v[206:209], v[52:55]
	v_mfma_f32_16x16x32_bf16 v[48:51], v[164:167], v[206:209], v[48:51]
	v_mfma_f32_16x16x32_bf16 v[36:39], v[136:139], v[214:217], v[36:39]
	v_mfma_f32_16x16x32_bf16 v[32:35], v[164:167], v[214:217], v[32:35]
	v_mfma_f32_16x16x32_bf16 v[20:23], v[136:139], v[222:225], v[20:23]
	v_mfma_f32_16x16x32_bf16 v[16:19], v[164:167], v[222:225], v[16:19]
	s_setprio 0
	s_setprio 1
	v_mfma_f32_16x16x32_bf16 v[44:47], v[168:171], v[194:197], v[44:47]
	v_mfma_f32_16x16x32_bf16 v[40:43], v[176:179], v[194:197], v[40:43]
	v_mfma_f32_16x16x32_bf16 v[28:31], v[168:171], v[202:205], v[28:31]
	v_mfma_f32_16x16x32_bf16 v[24:27], v[176:179], v[202:205], v[24:27]
	v_mfma_f32_16x16x32_bf16 v[12:15], v[168:171], v[210:213], v[12:15]
	v_mfma_f32_16x16x32_bf16 v[8:11], v[176:179], v[210:213], v[8:11]
	v_mfma_f32_16x16x32_bf16 v[4:7], v[168:171], v[218:221], v[4:7]
	v_mfma_f32_16x16x32_bf16 v[0:3], v[176:179], v[218:221], v[0:3]
	v_mfma_f32_16x16x32_bf16 v[44:47], v[172:175], v[198:201], v[44:47]
	v_mfma_f32_16x16x32_bf16 v[40:43], v[180:183], v[198:201], v[40:43]
	v_mfma_f32_16x16x32_bf16 v[28:31], v[172:175], v[206:209], v[28:31]
	v_mfma_f32_16x16x32_bf16 v[24:27], v[180:183], v[206:209], v[24:27]
	v_mfma_f32_16x16x32_bf16 v[12:15], v[172:175], v[214:217], v[12:15]
	v_mfma_f32_16x16x32_bf16 v[8:11], v[180:183], v[214:217], v[8:11]
	v_mfma_f32_16x16x32_bf16 v[4:7], v[172:175], v[222:225], v[4:7]
	v_mfma_f32_16x16x32_bf16 v[0:3], v[180:183], v[222:225], v[0:3]
	s_setprio 0
	s_barrier
	s_add_i32 s8, 16, 0x18000
	v_add_u32_e32 v96, s8, v147
	s_add_i32 s25, 16, 0x1c000
	ds_read_b128 v[132:135], v96
	ds_read_b128 v[136:139], v96 offset:1024
	ds_read_b128 v[160:163], v96 offset:2048
	ds_read_b128 v[164:167], v96 offset:3072
	v_add_u32_e32 v96, s25, v147
	ds_read_b128 v[168:171], v96
	ds_read_b128 v[172:175], v96 offset:1024
	ds_read_b128 v[176:179], v96 offset:2048
	ds_read_b128 v[180:183], v96 offset:3072
	s_add_u32 s18, s18, s4
	s_addc_u32 s19, s19, s5
	s_mov_b32 m0, s49
	v_lshl_add_u64 v[102:103], s[18:19], 0, v[140:141]
	ds_read_b128 v[194:197], v150 offset:32768
	ds_read_b128 v[198:201], v150 offset:33792
	ds_read_b128 v[202:205], v150 offset:34816
	ds_read_b128 v[206:209], v150 offset:35840
	ds_read_b128 v[210:213], v150 offset:36864
	ds_read_b128 v[214:217], v150 offset:37888
	ds_read_b128 v[218:221], v150 offset:38912
	ds_read_b128 v[222:225], v150 offset:39936
	global_load_lds_dwordx4 v[102:103], off
	v_lshl_add_u64 v[102:103], s[18:19], 0, v[144:145]
	s_mov_b32 m0, s50
	s_nop 0
	global_load_lds_dwordx4 v[102:103], off
	s_waitcnt vmcnt(8)
	s_waitcnt lgkmcnt(0)
	s_barrier
	s_setprio 1
	s_waitcnt lgkmcnt(0)
	v_mfma_f32_16x16x32_bf16 v[128:131], v[132:135], v[194:197], v[128:131]
	v_mfma_f32_16x16x32_bf16 v[124:127], v[160:163], v[194:197], v[124:127]
	v_mfma_f32_16x16x32_bf16 v[120:123], v[132:135], v[202:205], v[120:123]
	v_mfma_f32_16x16x32_bf16 v[112:115], v[160:163], v[202:205], v[112:115]
	v_mfma_f32_16x16x32_bf16 v[102:105], v[132:135], v[210:213], v[104:107]
	v_mfma_f32_16x16x32_bf16 v[92:95], v[160:163], v[210:213], v[92:95]
	v_mfma_f32_16x16x32_bf16 v[84:87], v[132:135], v[218:221], v[84:87]
	v_mfma_f32_16x16x32_bf16 v[76:79], v[160:163], v[218:221], v[76:79]
	v_mfma_f32_16x16x32_bf16 v[128:131], v[136:139], v[198:201], v[128:131]
	v_mfma_f32_16x16x32_bf16 v[124:127], v[164:167], v[198:201], v[124:127]
	v_mfma_f32_16x16x32_bf16 v[120:123], v[136:139], v[206:209], v[120:123]
	v_mfma_f32_16x16x32_bf16 v[112:115], v[164:167], v[206:209], v[112:115]
	v_mfma_f32_16x16x32_bf16 v[104:107], v[136:139], v[214:217], v[102:105]
	v_mfma_f32_16x16x32_bf16 v[92:95], v[164:167], v[214:217], v[92:95]
	v_mfma_f32_16x16x32_bf16 v[84:87], v[136:139], v[222:225], v[84:87]
	v_mfma_f32_16x16x32_bf16 v[76:79], v[164:167], v[222:225], v[76:79]
	s_setprio 0
	s_setprio 1
	v_mfma_f32_16x16x32_bf16 v[116:119], v[168:171], v[194:197], v[116:119]
	v_mfma_f32_16x16x32_bf16 v[108:111], v[176:179], v[194:197], v[108:111]
	v_mfma_f32_16x16x32_bf16 v[98:101], v[168:171], v[202:205], v[98:101]
	v_mfma_f32_16x16x32_bf16 v[88:91], v[176:179], v[202:205], v[88:91]
	v_mfma_f32_16x16x32_bf16 v[80:83], v[168:171], v[210:213], v[80:83]
	v_mfma_f32_16x16x32_bf16 v[72:75], v[176:179], v[210:213], v[72:75]
	v_mfma_f32_16x16x32_bf16 v[68:71], v[168:171], v[218:221], v[68:71]
	v_mfma_f32_16x16x32_bf16 v[64:67], v[176:179], v[218:221], v[64:67]
	v_mfma_f32_16x16x32_bf16 v[116:119], v[172:175], v[198:201], v[116:119]
	v_mfma_f32_16x16x32_bf16 v[108:111], v[180:183], v[198:201], v[108:111]
	v_mfma_f32_16x16x32_bf16 v[100:103], v[172:175], v[206:209], v[98:101]
	v_mfma_f32_16x16x32_bf16 v[88:91], v[180:183], v[206:209], v[88:91]
	v_mfma_f32_16x16x32_bf16 v[80:83], v[172:175], v[214:217], v[80:83]
	v_mfma_f32_16x16x32_bf16 v[72:75], v[180:183], v[214:217], v[72:75]
	v_mfma_f32_16x16x32_bf16 v[68:71], v[172:175], v[222:225], v[68:71]
	v_mfma_f32_16x16x32_bf16 v[64:67], v[180:183], v[222:225], v[64:67]
	s_setprio 0
	s_barrier
; #define PG8_STAGE(bufoff, gbase, voff) do { _Pragma("unroll") for (int _i = 0; _i < 2; ++_i) \
;         __builtin_amdgcn_global_load_lds((const unsigned*)((const char*)(gbase) + (voff)[_i]), (PG8_LAS unsigned*)(lds + (bufoff) + ldsw + _i * 8192), 16, 0, 0); } while (0)
; #define PG8_LDA(dst, b, h) do { _Pragma("unroll") for (int m = 0; m < 4; ++m) _Pragma("unroll") for (int k = 0; k < 2; ++k) dst[m][k] = *(const PG8_LAS bf16x8*)(lds + PG8_SA(b, h) + aoff + m * 2048 + k * 1024); } while (0)
; #define PG8_MMA(ai, bj, At, Bt) do { __builtin_amdgcn_s_setprio(1); _Pragma("unroll") for (int m = 0; m < 4; ++m) _Pragma("unroll") for (int n = 0; n < 2; ++n) _Pragma("unroll") for (int k = 0; k < 2; ++k) \
;         acc[ai][bj][m][n] = __builtin_amdgcn_mfma_f32_16x16x32_bf16(Bt[n][k], At[m][k], acc[ai][bj][m][n], 0, 0, 0); __builtin_amdgcn_s_setprio(0); } while (0)
; #define PG8_WAIT_V(n) asm volatile("s_waitcnt vmcnt(" #n ")" ::: "memory")
; #define PG8_WAIT_L(n) asm volatile("s_waitcnt lgkmcnt(" #n ")" ::: "memory")
; #define PG8_BAR __builtin_amdgcn_s_barrier()
; #define PG8_SCHED __builtin_amdgcn_sched_barrier(0)
; template <class Epi, class Sched, bool ALIGN_EPI = false, bool SP2 = false>
; __device__ __forceinline__ void gemm_phase(PG8_LAS unsigned char* lds, const Gemm g, const Sched& S, const Epi& E, int wid_s_) {
;     ...
;         for (int t = 0; t < nt; t += 2) {
;             const bool last = (t == nt - 2);
;             const char* a1 = cA + (size_t)(t + 1) * kstep;
;             const char* a2 = last ? nA : cA + (size_t)(t + 2) * kstep; const char* b2 = last ? nB : cB + (size_t)(t + 2) * kstep;
;     ...
;             PG8_LDA(At, 1, 1); PG8_STAGE(PG8_SB(1, 0), b3, voffB); PG8_STAGE(PG8_SB(1, 1), b3 + hstep, voffB); PG8_STAGE(PG8_SA(1, 0), a3, voffA);
;             PG8_WAIT_V(8); PG8_WAIT_L(0); PG8_BAR; PG8_MMA(1, 0, At, B0); PG8_MMA(1, 1, At, B1); PG8_BAR; PG8_SCHED;
	s_add_i32 s8, s8, s40
	v_lshl_add_u64 v[98:99], v[158:159], 0, s[42:43]
	s_mov_b32 m0, s8
	ds_read_b128 v[194:197], v150 offset:49152
	ds_read_b128 v[198:201], v150 offset:50176
	ds_read_b128 v[202:205], v150 offset:51200
	ds_read_b128 v[206:209], v150 offset:52224
	ds_read_b128 v[210:213], v150 offset:53248
	ds_read_b128 v[214:217], v150 offset:54272
	ds_read_b128 v[218:221], v150 offset:55296
	ds_read_b128 v[222:225], v150 offset:56320
	global_load_lds_dwordx4 v[98:99], off
	v_lshl_add_u64 v[98:99], v[188:189], 0, s[42:43]
	s_add_i32 m0, s8, 0x2000
	s_add_i32 s8, s25, s40
	global_load_lds_dwordx4 v[98:99], off
	v_lshl_add_u64 v[98:99], v[226:227], 0, s[42:43]
	s_mov_b32 m0, s8
	s_nop 0
	global_load_lds_dwordx4 v[98:99], off
	v_lshl_add_u64 v[98:99], v[228:229], 0, s[42:43]
	s_add_i32 m0, s8, 0x2000
	s_nop 0
	global_load_lds_dwordx4 v[98:99], off
	v_lshl_add_u64 v[98:99], v[230:231], 0, s[42:43]
	s_mov_b32 m0, s85
	s_nop 0
	global_load_lds_dwordx4 v[98:99], off
	v_lshl_add_u64 v[98:99], v[232:233], 0, s[42:43]
	s_mov_b32 m0, s86
	s_nop 0
	global_load_lds_dwordx4 v[98:99], off
	s_waitcnt vmcnt(8)
	s_waitcnt lgkmcnt(0)
	s_barrier
	s_setprio 1
	s_waitcnt lgkmcnt(0)
	v_mfma_f32_16x16x32_bf16 v[60:63], v[132:135], v[194:197], v[60:63]
	v_mfma_f32_16x16x32_bf16 v[56:59], v[160:163], v[194:197], v[56:59]
	v_mfma_f32_16x16x32_bf16 v[52:55], v[132:135], v[202:205], v[52:55]
	v_mfma_f32_16x16x32_bf16 v[48:51], v[160:163], v[202:205], v[48:51]
	v_mfma_f32_16x16x32_bf16 v[36:39], v[132:135], v[210:213], v[36:39]
	v_mfma_f32_16x16x32_bf16 v[32:35], v[160:163], v[210:213], v[32:35]
	v_mfma_f32_16x16x32_bf16 v[20:23], v[132:135], v[218:221], v[20:23]
	v_mfma_f32_16x16x32_bf16 v[16:19], v[160:163], v[218:221], v[16:19]
	v_mfma_f32_16x16x32_bf16 v[60:63], v[136:139], v[198:201], v[60:63]
	v_mfma_f32_16x16x32_bf16 v[56:59], v[164:167], v[198:201], v[56:59]
	v_mfma_f32_16x16x32_bf16 v[52:55], v[136:139], v[206:209], v[52:55]
	v_mfma_f32_16x16x32_bf16 v[48:51], v[164:167], v[206:209], v[48:51]
	v_mfma_f32_16x16x32_bf16 v[36:39], v[136:139], v[214:217], v[36:39]
	v_mfma_f32_16x16x32_bf16 v[32:35], v[164:167], v[214:217], v[32:35]
	v_mfma_f32_16x16x32_bf16 v[20:23], v[136:139], v[222:225], v[20:23]
	v_mfma_f32_16x16x32_bf16 v[16:19], v[164:167], v[222:225], v[16:19]
	s_setprio 0
	s_setprio 1
	v_mfma_f32_16x16x32_bf16 v[44:47], v[168:171], v[194:197], v[44:47]
	v_mfma_f32_16x16x32_bf16 v[40:43], v[176:179], v[194:197], v[40:43]
	v_mfma_f32_16x16x32_bf16 v[28:31], v[168:171], v[202:205], v[28:31]
	v_mfma_f32_16x16x32_bf16 v[24:27], v[176:179], v[202:205], v[24:27]
	v_mfma_f32_16x16x32_bf16 v[12:15], v[168:171], v[210:213], v[12:15]
	v_mfma_f32_16x16x32_bf16 v[8:11], v[176:179], v[210:213], v[8:11]
	v_mfma_f32_16x16x32_bf16 v[4:7], v[168:171], v[218:221], v[4:7]
	v_mfma_f32_16x16x32_bf16 v[0:3], v[176:179], v[218:221], v[0:3]
	v_mfma_f32_16x16x32_bf16 v[44:47], v[172:175], v[198:201], v[44:47]
	v_mfma_f32_16x16x32_bf16 v[40:43], v[180:183], v[198:201], v[40:43]
	v_mfma_f32_16x16x32_bf16 v[28:31], v[172:175], v[206:209], v[28:31]
	v_mfma_f32_16x16x32_bf16 v[24:27], v[180:183], v[206:209], v[24:27]
	v_mfma_f32_16x16x32_bf16 v[12:15], v[172:175], v[214:217], v[12:15]
	v_mfma_f32_16x16x32_bf16 v[8:11], v[180:183], v[214:217], v[8:11]
	v_mfma_f32_16x16x32_bf16 v[4:7], v[172:175], v[222:225], v[4:7]
	v_mfma_f32_16x16x32_bf16 v[0:3], v[180:183], v[222:225], v[0:3]
	s_setprio 0
	s_barrier
	s_add_u32 vcc_lo, vcc_lo, 0x100
	s_addc_u32 vcc_hi, vcc_hi, 0
	s_add_u32 s2, s2, 0x100
	s_addc_u32 s3, s3, 0
	s_cmp_ge_i32 s91, s87
	s_mov_b32 s18, s91
	s_cbranch_scc0 .LBB0_886
	v_readlane_b32 s78, v255, 54
	v_readlane_b32 s79, v255, 55
	s_and_b64 vcc, exec, s[12:13]
	s_cbranch_vccnz .LBB0_891
	s_branch .LBB0_892

; #define PG8_STAGE(bufoff, gbase, voff) do { _Pragma("unroll") for (int _i = 0; _i < 2; ++_i) \
;         __builtin_amdgcn_global_load_lds((const unsigned*)((const char*)(gbase) + (voff)[_i]), (PG8_LAS unsigned*)(lds + (bufoff) + ldsw + _i * 8192), 16, 0, 0); } while (0)
; #define PG8_LDA(dst, b, h) do { _Pragma("unroll") for (int m = 0; m < 4; ++m) _Pragma("unroll") for (int k = 0; k < 2; ++k) dst[m][k] = *(const PG8_LAS bf16x8*)(lds + PG8_SA(b, h) + aoff + m * 2048 + k * 1024); } while (0)
; #define PG8_LDB(dst, b, h) do { _Pragma("unroll") for (int n = 0; n < 2; ++n) _Pragma("unroll") for (int k = 0; k < 2; ++k) dst[n][k] = *(const PG8_LAS bf16x8*)(lds + PG8_SB(b, h) + boff + n * 2048 + k * 1024); } while (0)
; #define PG8_MMA(ai, bj, At, Bt) do { __builtin_amdgcn_s_setprio(1); _Pragma("unroll") for (int m = 0; m < 4; ++m) _Pragma("unroll") for (int n = 0; n < 2; ++n) _Pragma("unroll") for (int k = 0; k < 2; ++k) \
;         acc[ai][bj][m][n] = __builtin_amdgcn_mfma_f32_16x16x32_bf16(Bt[n][k], At[m][k], acc[ai][bj][m][n], 0, 0, 0); __builtin_amdgcn_s_setprio(0); } while (0)
; #define PG8_WAIT_V(n) asm volatile("s_waitcnt vmcnt(" #n ")" ::: "memory")
; #define PG8_WAIT_L(n) asm volatile("s_waitcnt lgkmcnt(" #n ")" ::: "memory")
; template <class Epi, class Sched, bool ALIGN_EPI = false, bool SP2 = false>
; __device__ __forceinline__ void gemm_phase(PG8_LAS unsigned char* lds, const Gemm g, const Sched& S, const Epi& E, int wid_s_) {
;     ...
;             const bool last = (t == nt - 2);
;             const char* a1 = cA + (size_t)(t + 1) * kstep;
;             const char* a2 = last ? nA : cA + (size_t)(t + 2) * kstep; const char* b2 = last ? nB : cB + (size_t)(t + 2) * kstep;
;             const char* a3 = a2 + kstep; const char* b3 = b2 + kstep;
;             if (last && has_next) S.a_ready(nxt);
;             if constexpr (SP2) {
;             PG8_LDB(B0, 0, 0); PG8_LDB(B1, 0, 1); PG8_SCHED; PG8_LDA(At, 0, 0); PG8_STAGE(PG8_SA(1, 1), a1 + hstep, voffA);
;             PG8_WAIT_V(8); PG8_WAIT_L(0); PG8_BAR; PG8_MMA(0, 0, At, B0); PG8_MMA(0, 1, At, B1); PG8_BAR; PG8_SCHED;
;             PG8_LDA(At, 0, 1); PG8_STAGE(PG8_SB(0, 0), b2, voffB); PG8_STAGE(PG8_SB(0, 1), b2 + hstep, voffB); PG8_STAGE(PG8_SA(0, 0), a2, voffA);
;             PG8_WAIT_V(8); PG8_WAIT_L(0); PG8_BAR; PG8_MMA(1, 0, At, B0); PG8_MMA(1, 1, At, B1); PG8_BAR; PG8_SCHED;
.LBB0_1276:
	s_add_i32 s84, s22, 2
	s_add_u32 s78, s20, 0x80
	s_addc_u32 s23, s21, 0
	s_add_i32 s85, 16, 0x10000
	s_cmp_eq_u32 s86, s22
	s_cselect_b32 s23, s17, s23
	s_cselect_b32 s22, s16, s78
	v_add_u32_e32 v150, s85, v147
	s_cselect_b32 s79, s19, vcc_hi
	s_cselect_b32 s78, s18, vcc_lo
	s_add_i32 s8, 16, 0x14000
	ds_read_b128 v[130:133], v150
	ds_read_b128 v[134:137], v150 offset:1024
	ds_read_b128 v[154:157], v150 offset:2048
	ds_read_b128 v[158:161], v150 offset:3072
	v_add_u32_e32 v150, s8, v147
	ds_read_b128 v[162:165], v150
	ds_read_b128 v[166:169], v150 offset:1024
	ds_read_b128 v[170:173], v150 offset:2048
	ds_read_b128 v[174:177], v150 offset:3072
	v_lshl_add_u64 v[150:151], s[20:21], 0, v[152:153]
	s_add_i32 m0, s40, 0xc000
	ds_read_b128 v[180:183], v149
	ds_read_b128 v[196:199], v149 offset:1024
	ds_read_b128 v[200:203], v149 offset:2048
	ds_read_b128 v[204:207], v149 offset:3072
	ds_read_b128 v[208:211], v149 offset:4096
	ds_read_b128 v[212:215], v149 offset:5120
	ds_read_b128 v[216:219], v149 offset:6144
	ds_read_b128 v[220:223], v149 offset:7168
	global_load_lds_dwordx4 v[150:151], off
	v_lshl_add_u64 v[150:151], s[20:21], 0, v[144:145]
	s_add_i32 m0, s40, 0xe000
	s_nop 0
	global_load_lds_dwordx4 v[150:151], off
	s_waitcnt vmcnt(8)
	s_waitcnt lgkmcnt(0)
	s_barrier
	s_setprio 1
	s_waitcnt lgkmcnt(0)
	v_mfma_f32_16x16x32_bf16 v[122:125], v[130:133], v[180:183], v[122:125]
	v_mfma_f32_16x16x32_bf16 v[126:129], v[154:157], v[180:183], v[126:129]
	v_mfma_f32_16x16x32_bf16 v[118:121], v[130:133], v[200:203], v[118:121]
	v_mfma_f32_16x16x32_bf16 v[114:117], v[154:157], v[200:203], v[114:117]
	v_mfma_f32_16x16x32_bf16 v[110:113], v[130:133], v[208:211], v[110:113]
	v_mfma_f32_16x16x32_bf16 v[106:109], v[154:157], v[208:211], v[106:109]
	v_mfma_f32_16x16x32_bf16 v[102:105], v[130:133], v[216:219], v[102:105]
	v_mfma_f32_16x16x32_bf16 v[98:101], v[154:157], v[216:219], v[98:101]
	v_mfma_f32_16x16x32_bf16 v[122:125], v[134:137], v[196:199], v[122:125]
	v_mfma_f32_16x16x32_bf16 v[126:129], v[158:161], v[196:199], v[126:129]
	v_mfma_f32_16x16x32_bf16 v[118:121], v[134:137], v[204:207], v[118:121]
	v_mfma_f32_16x16x32_bf16 v[114:117], v[158:161], v[204:207], v[114:117]
	v_mfma_f32_16x16x32_bf16 v[110:113], v[134:137], v[212:215], v[110:113]
	v_mfma_f32_16x16x32_bf16 v[106:109], v[158:161], v[212:215], v[106:109]
	v_mfma_f32_16x16x32_bf16 v[102:105], v[134:137], v[220:223], v[102:105]
	v_mfma_f32_16x16x32_bf16 v[98:101], v[158:161], v[220:223], v[98:101]
	s_setprio 0
	s_setprio 1
	v_mfma_f32_16x16x32_bf16 v[60:63], v[162:165], v[180:183], v[60:63]
	v_mfma_f32_16x16x32_bf16 v[56:59], v[170:173], v[180:183], v[56:59]
	v_mfma_f32_16x16x32_bf16 v[52:55], v[162:165], v[200:203], v[52:55]
	v_mfma_f32_16x16x32_bf16 v[48:51], v[170:173], v[200:203], v[48:51]
	v_mfma_f32_16x16x32_bf16 v[44:47], v[162:165], v[208:211], v[44:47]
	v_mfma_f32_16x16x32_bf16 v[40:43], v[170:173], v[208:211], v[40:43]
	v_mfma_f32_16x16x32_bf16 v[36:39], v[162:165], v[216:219], v[36:39]
	v_mfma_f32_16x16x32_bf16 v[32:35], v[170:173], v[216:219], v[32:35]
	v_mfma_f32_16x16x32_bf16 v[60:63], v[166:169], v[196:199], v[60:63]
	v_mfma_f32_16x16x32_bf16 v[56:59], v[174:177], v[196:199], v[56:59]
	v_mfma_f32_16x16x32_bf16 v[52:55], v[166:169], v[204:207], v[52:55]
	v_mfma_f32_16x16x32_bf16 v[48:51], v[174:177], v[204:207], v[48:51]
	v_mfma_f32_16x16x32_bf16 v[44:47], v[166:169], v[212:215], v[44:47]
	v_mfma_f32_16x16x32_bf16 v[40:43], v[174:177], v[212:215], v[40:43]
	v_mfma_f32_16x16x32_bf16 v[36:39], v[166:169], v[220:223], v[36:39]
	v_mfma_f32_16x16x32_bf16 v[32:35], v[174:177], v[220:223], v[32:35]
	s_setprio 0
	s_barrier
	s_add_i32 s9, s85, s37
	v_lshl_add_u64 v[150:151], s[78:79], 0, v[96:97]
	s_mov_b32 m0, s9
	ds_read_b128 v[180:183], v149 offset:16384
	ds_read_b128 v[196:199], v149 offset:17408
	ds_read_b128 v[200:203], v149 offset:18432
	ds_read_b128 v[204:207], v149 offset:19456
	ds_read_b128 v[208:211], v149 offset:20480
	ds_read_b128 v[212:215], v149 offset:21504
	ds_read_b128 v[216:219], v149 offset:22528
	ds_read_b128 v[220:223], v149 offset:23552
	global_load_lds_dwordx4 v[150:151], off
	s_add_i32 m0, s9, 0x2000
	v_lshl_add_u64 v[178:179], s[78:79], 0, v[138:139]
	s_add_u32 s78, s78, s2
	s_addc_u32 s79, s79, s3
	s_add_i32 s8, s8, s37
	global_load_lds_dwordx4 v[178:179], off
	v_lshl_add_u64 v[188:189], s[78:79], 0, v[96:97]
	s_mov_b32 m0, s8
	v_lshl_add_u64 v[194:195], s[78:79], 0, v[138:139]
	global_load_lds_dwordx4 v[188:189], off
	s_add_i32 m0, s8, 0x2000
	v_lshl_add_u64 v[224:225], s[22:23], 0, v[142:143]
	global_load_lds_dwordx4 v[194:195], off
	s_mov_b32 m0, s40
	v_lshl_add_u64 v[226:227], s[22:23], 0, v[140:141]
	global_load_lds_dwordx4 v[224:225], off
	s_mov_b32 m0, s41
	s_nop 0
	global_load_lds_dwordx4 v[226:227], off
	s_waitcnt vmcnt(8)
	s_waitcnt lgkmcnt(0)
	s_barrier
; #define PG8_STAGE(bufoff, gbase, voff) do { _Pragma("unroll") for (int _i = 0; _i < 2; ++_i) \
;         __builtin_amdgcn_global_load_lds((const unsigned*)((const char*)(gbase) + (voff)[_i]), (PG8_LAS unsigned*)(lds + (bufoff) + ldsw + _i * 8192), 16, 0, 0); } while (0)
; #define PG8_LDA(dst, b, h) do { _Pragma("unroll") for (int m = 0; m < 4; ++m) _Pragma("unroll") for (int k = 0; k < 2; ++k) dst[m][k] = *(const PG8_LAS bf16x8*)(lds + PG8_SA(b, h) + aoff + m * 2048 + k * 1024); } while (0)
; #define PG8_LDB(dst, b, h) do { _Pragma("unroll") for (int n = 0; n < 2; ++n) _Pragma("unroll") for (int k = 0; k < 2; ++k) dst[n][k] = *(const PG8_LAS bf16x8*)(lds + PG8_SB(b, h) + boff + n * 2048 + k * 1024); } while (0)
; #define PG8_MMA(ai, bj, At, Bt) do { __builtin_amdgcn_s_setprio(1); _Pragma("unroll") for (int m = 0; m < 4; ++m) _Pragma("unroll") for (int n = 0; n < 2; ++n) _Pragma("unroll") for (int k = 0; k < 2; ++k) \
;         acc[ai][bj][m][n] = __builtin_amdgcn_mfma_f32_16x16x32_bf16(Bt[n][k], At[m][k], acc[ai][bj][m][n], 0, 0, 0); __builtin_amdgcn_s_setprio(0); } while (0)
; #define PG8_WAIT_V(n) asm volatile("s_waitcnt vmcnt(" #n ")" ::: "memory")
; #define PG8_WAIT_L(n) asm volatile("s_waitcnt lgkmcnt(" #n ")" ::: "memory")
; #define PG8_BAR __builtin_amdgcn_s_barrier()
; #define PG8_SCHED __builtin_amdgcn_sched_barrier(0)
; template <class Epi, class Sched, bool ALIGN_EPI = false, bool SP2 = false>
; __device__ __forceinline__ void gemm_phase(PG8_LAS unsigned char* lds, const Gemm g, const Sched& S, const Epi& E, int wid_s_) {
;     ...
;             PG8_WAIT_V(8); PG8_WAIT_L(0); PG8_BAR; PG8_MMA(1, 0, At, B0); PG8_MMA(1, 1, At, B1); PG8_BAR; PG8_SCHED;
;             PG8_LDB(B0, 1, 0); PG8_LDB(B1, 1, 1); PG8_SCHED; PG8_LDA(At, 1, 0); PG8_STAGE(PG8_SA(0, 1), a2 + hstep, voffA);
;             PG8_WAIT_V(8); PG8_WAIT_L(0); PG8_BAR; PG8_MMA(0, 0, At, B0); PG8_MMA(0, 1, At, B1); PG8_BAR; PG8_SCHED;
	s_setprio 1
	s_waitcnt lgkmcnt(0)
	v_mfma_f32_16x16x32_bf16 v[92:95], v[130:133], v[180:183], v[92:95]
	v_mfma_f32_16x16x32_bf16 v[88:91], v[154:157], v[180:183], v[88:91]
	v_mfma_f32_16x16x32_bf16 v[84:87], v[130:133], v[200:203], v[84:87]
	v_mfma_f32_16x16x32_bf16 v[80:83], v[154:157], v[200:203], v[80:83]
	v_mfma_f32_16x16x32_bf16 v[76:79], v[130:133], v[208:211], v[76:79]
	v_mfma_f32_16x16x32_bf16 v[72:75], v[154:157], v[208:211], v[72:75]
	v_mfma_f32_16x16x32_bf16 v[68:71], v[130:133], v[216:219], v[68:71]
	v_mfma_f32_16x16x32_bf16 v[64:67], v[154:157], v[216:219], v[64:67]
	v_mfma_f32_16x16x32_bf16 v[92:95], v[134:137], v[196:199], v[92:95]
	v_mfma_f32_16x16x32_bf16 v[88:91], v[158:161], v[196:199], v[88:91]
	v_mfma_f32_16x16x32_bf16 v[84:87], v[134:137], v[204:207], v[84:87]
	v_mfma_f32_16x16x32_bf16 v[80:83], v[158:161], v[204:207], v[80:83]
	v_mfma_f32_16x16x32_bf16 v[76:79], v[134:137], v[212:215], v[76:79]
	v_mfma_f32_16x16x32_bf16 v[72:75], v[158:161], v[212:215], v[72:75]
	v_mfma_f32_16x16x32_bf16 v[68:71], v[134:137], v[220:223], v[68:71]
	v_mfma_f32_16x16x32_bf16 v[64:67], v[158:161], v[220:223], v[64:67]
	s_setprio 0
	s_setprio 1
	v_mfma_f32_16x16x32_bf16 v[28:31], v[162:165], v[180:183], v[28:31]
	v_mfma_f32_16x16x32_bf16 v[24:27], v[170:173], v[180:183], v[24:27]
	v_mfma_f32_16x16x32_bf16 v[20:23], v[162:165], v[200:203], v[20:23]
	v_mfma_f32_16x16x32_bf16 v[16:19], v[170:173], v[200:203], v[16:19]
	v_mfma_f32_16x16x32_bf16 v[12:15], v[162:165], v[208:211], v[12:15]
	v_mfma_f32_16x16x32_bf16 v[8:11], v[170:173], v[208:211], v[8:11]
	v_mfma_f32_16x16x32_bf16 v[4:7], v[162:165], v[216:219], v[4:7]
	v_mfma_f32_16x16x32_bf16 v[0:3], v[170:173], v[216:219], v[0:3]
	v_mfma_f32_16x16x32_bf16 v[28:31], v[166:169], v[196:199], v[28:31]
	v_mfma_f32_16x16x32_bf16 v[24:27], v[174:177], v[196:199], v[24:27]
	v_mfma_f32_16x16x32_bf16 v[20:23], v[166:169], v[204:207], v[20:23]
	v_mfma_f32_16x16x32_bf16 v[16:19], v[174:177], v[204:207], v[16:19]
	v_mfma_f32_16x16x32_bf16 v[12:15], v[166:169], v[212:215], v[12:15]
	v_mfma_f32_16x16x32_bf16 v[8:11], v[174:177], v[212:215], v[8:11]
	v_mfma_f32_16x16x32_bf16 v[4:7], v[166:169], v[220:223], v[4:7]
	v_mfma_f32_16x16x32_bf16 v[0:3], v[174:177], v[220:223], v[0:3]
	s_setprio 0
	s_barrier
	s_add_i32 s8, 16, 0x18000
	s_add_i32 s9, 16, 0x1c000
	v_add_u32_e32 v158, s8, v147
	v_add_u32_e32 v174, s9, v147
	ds_read_b128 v[130:133], v158
	ds_read_b128 v[134:137], v158 offset:1024
	ds_read_b128 v[154:157], v158 offset:2048
	ds_read_b128 v[158:161], v158 offset:3072
	ds_read_b128 v[162:165], v174
	ds_read_b128 v[166:169], v174 offset:1024
	ds_read_b128 v[170:173], v174 offset:2048
	ds_read_b128 v[174:177], v174 offset:3072
	s_add_u32 s22, s22, s2
	s_addc_u32 s23, s23, s3
	s_mov_b32 m0, s48
	v_lshl_add_u64 v[228:229], s[22:23], 0, v[142:143]
	ds_read_b128 v[180:183], v149 offset:32768
	ds_read_b128 v[196:199], v149 offset:33792
	ds_read_b128 v[200:203], v149 offset:34816
	ds_read_b128 v[204:207], v149 offset:35840
	ds_read_b128 v[208:211], v149 offset:36864
	ds_read_b128 v[212:215], v149 offset:37888
	ds_read_b128 v[216:219], v149 offset:38912
	ds_read_b128 v[220:223], v149 offset:39936
	global_load_lds_dwordx4 v[228:229], off
	v_lshl_add_u64 v[228:229], s[22:23], 0, v[140:141]
	s_mov_b32 m0, s49
	s_nop 0
	global_load_lds_dwordx4 v[228:229], off
	s_waitcnt vmcnt(8)
	s_waitcnt lgkmcnt(0)
	s_barrier
	s_setprio 1
	s_waitcnt lgkmcnt(0)
	v_mfma_f32_16x16x32_bf16 v[122:125], v[130:133], v[180:183], v[122:125]
	v_mfma_f32_16x16x32_bf16 v[126:129], v[154:157], v[180:183], v[126:129]
	v_mfma_f32_16x16x32_bf16 v[118:121], v[130:133], v[200:203], v[118:121]
	v_mfma_f32_16x16x32_bf16 v[114:117], v[154:157], v[200:203], v[114:117]
	v_mfma_f32_16x16x32_bf16 v[110:113], v[130:133], v[208:211], v[110:113]
	v_mfma_f32_16x16x32_bf16 v[106:109], v[154:157], v[208:211], v[106:109]
	v_mfma_f32_16x16x32_bf16 v[102:105], v[130:133], v[216:219], v[102:105]
	v_mfma_f32_16x16x32_bf16 v[98:101], v[154:157], v[216:219], v[98:101]
	v_mfma_f32_16x16x32_bf16 v[122:125], v[134:137], v[196:199], v[122:125]
	v_mfma_f32_16x16x32_bf16 v[126:129], v[158:161], v[196:199], v[126:129]
	v_mfma_f32_16x16x32_bf16 v[118:121], v[134:137], v[204:207], v[118:121]
	v_mfma_f32_16x16x32_bf16 v[114:117], v[158:161], v[204:207], v[114:117]
	v_mfma_f32_16x16x32_bf16 v[110:113], v[134:137], v[212:215], v[110:113]
	v_mfma_f32_16x16x32_bf16 v[106:109], v[158:161], v[212:215], v[106:109]
	v_mfma_f32_16x16x32_bf16 v[102:105], v[134:137], v[220:223], v[102:105]
	v_mfma_f32_16x16x32_bf16 v[98:101], v[158:161], v[220:223], v[98:101]
	s_setprio 0
	s_setprio 1
	v_mfma_f32_16x16x32_bf16 v[60:63], v[162:165], v[180:183], v[60:63]
	v_mfma_f32_16x16x32_bf16 v[56:59], v[170:173], v[180:183], v[56:59]
	v_mfma_f32_16x16x32_bf16 v[52:55], v[162:165], v[200:203], v[52:55]
	v_mfma_f32_16x16x32_bf16 v[48:51], v[170:173], v[200:203], v[48:51]
	v_mfma_f32_16x16x32_bf16 v[44:47], v[162:165], v[208:211], v[44:47]
	v_mfma_f32_16x16x32_bf16 v[40:43], v[170:173], v[208:211], v[40:43]
	v_mfma_f32_16x16x32_bf16 v[36:39], v[162:165], v[216:219], v[36:39]
	v_mfma_f32_16x16x32_bf16 v[32:35], v[170:173], v[216:219], v[32:35]
	v_mfma_f32_16x16x32_bf16 v[60:63], v[166:169], v[196:199], v[60:63]
	v_mfma_f32_16x16x32_bf16 v[56:59], v[174:177], v[196:199], v[56:59]
	v_mfma_f32_16x16x32_bf16 v[52:55], v[166:169], v[204:207], v[52:55]
	v_mfma_f32_16x16x32_bf16 v[48:51], v[174:177], v[204:207], v[48:51]
	v_mfma_f32_16x16x32_bf16 v[44:47], v[166:169], v[212:215], v[44:47]
	v_mfma_f32_16x16x32_bf16 v[40:43], v[174:177], v[212:215], v[40:43]
	v_mfma_f32_16x16x32_bf16 v[36:39], v[166:169], v[220:223], v[36:39]
	v_mfma_f32_16x16x32_bf16 v[32:35], v[174:177], v[220:223], v[32:35]
	s_setprio 0
	s_barrier
; #define PG8_STAGE(bufoff, gbase, voff) do { _Pragma("unroll") for (int _i = 0; _i < 2; ++_i) \
;         __builtin_amdgcn_global_load_lds((const unsigned*)((const char*)(gbase) + (voff)[_i]), (PG8_LAS unsigned*)(lds + (bufoff) + ldsw + _i * 8192), 16, 0, 0); } while (0)
; #define PG8_LDA(dst, b, h) do { _Pragma("unroll") for (int m = 0; m < 4; ++m) _Pragma("unroll") for (int k = 0; k < 2; ++k) dst[m][k] = *(const PG8_LAS bf16x8*)(lds + PG8_SA(b, h) + aoff + m * 2048 + k * 1024); } while (0)
; #define PG8_MMA(ai, bj, At, Bt) do { __builtin_amdgcn_s_setprio(1); _Pragma("unroll") for (int m = 0; m < 4; ++m) _Pragma("unroll") for (int n = 0; n < 2; ++n) _Pragma("unroll") for (int k = 0; k < 2; ++k) \
;         acc[ai][bj][m][n] = __builtin_amdgcn_mfma_f32_16x16x32_bf16(Bt[n][k], At[m][k], acc[ai][bj][m][n], 0, 0, 0); __builtin_amdgcn_s_setprio(0); } while (0)
; #define PG8_WAIT_V(n) asm volatile("s_waitcnt vmcnt(" #n ")" ::: "memory")
; #define PG8_WAIT_L(n) asm volatile("s_waitcnt lgkmcnt(" #n ")" ::: "memory")
; #define PG8_BAR __builtin_amdgcn_s_barrier()
; #define PG8_SCHED __builtin_amdgcn_sched_barrier(0)
; template <class Epi, class Sched, bool ALIGN_EPI = false, bool SP2 = false>
; __device__ __forceinline__ void gemm_phase(PG8_LAS unsigned char* lds, const Gemm g, const Sched& S, const Epi& E, int wid_s_) {
;     ...
;             PG8_LDA(At, 1, 1); PG8_STAGE(PG8_SB(1, 0), b3, voffB); PG8_STAGE(PG8_SB(1, 1), b3 + hstep, voffB); PG8_STAGE(PG8_SA(1, 0), a3, voffA);
;             PG8_WAIT_V(8); PG8_WAIT_L(0); PG8_BAR; PG8_MMA(1, 0, At, B0); PG8_MMA(1, 1, At, B1); PG8_BAR; PG8_SCHED;
	s_add_i32 s8, s8, s37
	v_lshl_add_u64 v[150:151], v[150:151], 0, s[42:43]
	s_mov_b32 m0, s8
	ds_read_b128 v[180:183], v149 offset:49152
	ds_read_b128 v[196:199], v149 offset:50176
	ds_read_b128 v[200:203], v149 offset:51200
	ds_read_b128 v[204:207], v149 offset:52224
	ds_read_b128 v[208:211], v149 offset:53248
	ds_read_b128 v[212:215], v149 offset:54272
	ds_read_b128 v[216:219], v149 offset:55296
	ds_read_b128 v[220:223], v149 offset:56320
	global_load_lds_dwordx4 v[150:151], off
	v_lshl_add_u64 v[150:151], v[178:179], 0, s[42:43]
	s_add_i32 m0, s8, 0x2000
	s_add_i32 s8, s9, s37
	global_load_lds_dwordx4 v[150:151], off
	v_lshl_add_u64 v[150:151], v[188:189], 0, s[42:43]
	s_mov_b32 m0, s8
	s_nop 0
	global_load_lds_dwordx4 v[150:151], off
	v_lshl_add_u64 v[150:151], v[194:195], 0, s[42:43]
	s_add_i32 m0, s8, 0x2000
	s_nop 0
	global_load_lds_dwordx4 v[150:151], off
	v_lshl_add_u64 v[150:151], v[224:225], 0, s[42:43]
	s_mov_b32 m0, s26
	s_nop 0
	global_load_lds_dwordx4 v[150:151], off
	v_lshl_add_u64 v[150:151], v[226:227], 0, s[42:43]
	s_mov_b32 m0, s50
	s_nop 0
	global_load_lds_dwordx4 v[150:151], off
	s_waitcnt vmcnt(8)
	s_waitcnt lgkmcnt(0)
	s_barrier
	s_setprio 1
	s_waitcnt lgkmcnt(0)
	v_mfma_f32_16x16x32_bf16 v[92:95], v[130:133], v[180:183], v[92:95]
	v_mfma_f32_16x16x32_bf16 v[88:91], v[154:157], v[180:183], v[88:91]
	v_mfma_f32_16x16x32_bf16 v[84:87], v[130:133], v[200:203], v[84:87]
	v_mfma_f32_16x16x32_bf16 v[80:83], v[154:157], v[200:203], v[80:83]
	v_mfma_f32_16x16x32_bf16 v[76:79], v[130:133], v[208:211], v[76:79]
	v_mfma_f32_16x16x32_bf16 v[72:75], v[154:157], v[208:211], v[72:75]
	v_mfma_f32_16x16x32_bf16 v[68:71], v[130:133], v[216:219], v[68:71]
	v_mfma_f32_16x16x32_bf16 v[64:67], v[154:157], v[216:219], v[64:67]
	v_mfma_f32_16x16x32_bf16 v[92:95], v[134:137], v[196:199], v[92:95]
	v_mfma_f32_16x16x32_bf16 v[88:91], v[158:161], v[196:199], v[88:91]
	v_mfma_f32_16x16x32_bf16 v[84:87], v[134:137], v[204:207], v[84:87]
	v_mfma_f32_16x16x32_bf16 v[80:83], v[158:161], v[204:207], v[80:83]
	v_mfma_f32_16x16x32_bf16 v[76:79], v[134:137], v[212:215], v[76:79]
	v_mfma_f32_16x16x32_bf16 v[72:75], v[158:161], v[212:215], v[72:75]
	v_mfma_f32_16x16x32_bf16 v[68:71], v[134:137], v[220:223], v[68:71]
	v_mfma_f32_16x16x32_bf16 v[64:67], v[158:161], v[220:223], v[64:67]
	s_setprio 0
	s_setprio 1
	v_mfma_f32_16x16x32_bf16 v[28:31], v[162:165], v[180:183], v[28:31]
	v_mfma_f32_16x16x32_bf16 v[24:27], v[170:173], v[180:183], v[24:27]
	v_mfma_f32_16x16x32_bf16 v[20:23], v[162:165], v[200:203], v[20:23]
	v_mfma_f32_16x16x32_bf16 v[16:19], v[170:173], v[200:203], v[16:19]
	v_mfma_f32_16x16x32_bf16 v[12:15], v[162:165], v[208:211], v[12:15]
	v_mfma_f32_16x16x32_bf16 v[8:11], v[170:173], v[208:211], v[8:11]
	v_mfma_f32_16x16x32_bf16 v[4:7], v[162:165], v[216:219], v[4:7]
	v_mfma_f32_16x16x32_bf16 v[0:3], v[170:173], v[216:219], v[0:3]
	v_mfma_f32_16x16x32_bf16 v[28:31], v[166:169], v[196:199], v[28:31]
	v_mfma_f32_16x16x32_bf16 v[24:27], v[174:177], v[196:199], v[24:27]
	v_mfma_f32_16x16x32_bf16 v[20:23], v[166:169], v[204:207], v[20:23]
	v_mfma_f32_16x16x32_bf16 v[16:19], v[174:177], v[204:207], v[16:19]
	v_mfma_f32_16x16x32_bf16 v[12:15], v[166:169], v[212:215], v[12:15]
	v_mfma_f32_16x16x32_bf16 v[8:11], v[174:177], v[212:215], v[8:11]
	v_mfma_f32_16x16x32_bf16 v[4:7], v[166:169], v[220:223], v[4:7]
	v_mfma_f32_16x16x32_bf16 v[0:3], v[174:177], v[220:223], v[0:3]
	s_setprio 0
	s_barrier
	s_add_u32 vcc_lo, vcc_lo, 0x100
	s_addc_u32 vcc_hi, vcc_hi, 0
	s_add_u32 s20, s20, 0x100
	s_addc_u32 s21, s21, 0
	s_cmp_ge_i32 s84, s51
	s_mov_b32 s22, s84
	s_cbranch_scc0 .LBB0_1276
	v_readlane_b32 s78, v255, 54
	v_readlane_b32 s79, v255, 55

; #define PG8_STAGE(bufoff, gbase, voff) do { _Pragma("unroll") for (int _i = 0; _i < 2; ++_i) \
;         __builtin_amdgcn_global_load_lds((const unsigned*)((const char*)(gbase) + (voff)[_i]), (PG8_LAS unsigned*)(lds + (bufoff) + ldsw + _i * 8192), 16, 0, 0); } while (0)
; #define PG8_LDA(dst, b, h) do { _Pragma("unroll") for (int m = 0; m < 4; ++m) _Pragma("unroll") for (int k = 0; k < 2; ++k) dst[m][k] = *(const PG8_LAS bf16x8*)(lds + PG8_SA(b, h) + aoff + m * 2048 + k * 1024); } while (0)
; #define PG8_LDB(dst, b, h) do { _Pragma("unroll") for (int n = 0; n < 2; ++n) _Pragma("unroll") for (int k = 0; k < 2; ++k) dst[n][k] = *(const PG8_LAS bf16x8*)(lds + PG8_SB(b, h) + boff + n * 2048 + k * 1024); } while (0)
; #define PG8_MMA(ai, bj, At, Bt) do { __builtin_amdgcn_s_setprio(1); _Pragma("unroll") for (int m = 0; m < 4; ++m) _Pragma("unroll") for (int n = 0; n < 2; ++n) _Pragma("unroll") for (int k = 0; k < 2; ++k) \
;         acc[ai][bj][m][n] = __builtin_amdgcn_mfma_f32_16x16x32_bf16(Bt[n][k], At[m][k], acc[ai][bj][m][n], 0, 0, 0); __builtin_amdgcn_s_setprio(0); } while (0)
; #define PG8_WAIT_V(n) asm volatile("s_waitcnt vmcnt(" #n ")" ::: "memory")
; #define PG8_WAIT_L(n) asm volatile("s_waitcnt lgkmcnt(" #n ")" ::: "memory")
; #define PG8_BAR __builtin_amdgcn_s_barrier()
; #define PG8_SCHED __builtin_amdgcn_sched_barrier(0)
; template <class Epi, class Sched, bool ALIGN_EPI = false, bool SP2 = false>
; __device__ __forceinline__ void gemm_phase(PG8_LAS unsigned char* lds, const Gemm g, const Sched& S, const Epi& E, int wid_s_) {
;     ...
;             PG8_LDB(B0, 0, 0); PG8_LDB(B1, 0, 1); PG8_SCHED; PG8_LDA(At, 0, 0); PG8_STAGE(PG8_SA(1, 1), a1 + hstep, voffA);
;             PG8_WAIT_V(8); PG8_WAIT_L(0); PG8_BAR; PG8_MMA(0, 0, At, B0); PG8_MMA(0, 1, At, B1); PG8_BAR; PG8_SCHED;
;             PG8_LDA(At, 0, 1); PG8_STAGE(PG8_SB(0, 0), b2, voffB); PG8_STAGE(PG8_SB(0, 1), b2 + hstep, voffB); PG8_STAGE(PG8_SA(0, 0), a2, voffA);
;             PG8_WAIT_V(8); PG8_WAIT_L(0); PG8_BAR; PG8_MMA(1, 0, At, B0); PG8_MMA(1, 1, At, B1); PG8_BAR; PG8_SCHED;
.LBB0_1393:
	s_add_i32 vcc_lo, s22, 2
	s_add_u32 s78, s20, 0x80
	s_addc_u32 s23, s21, 0
	s_add_i32 vcc_hi, 16, 0x10000
	s_cmp_eq_u32 s83, s22
	s_cselect_b32 s23, s3, s23
	s_cselect_b32 s22, s2, s78
	v_add_u32_e32 v150, vcc_hi, v147
	s_cselect_b32 s79, s19, s91
	s_cselect_b32 s78, s18, s90
	s_add_i32 s10, 16, 0x14000
	ds_read_b128 v[130:133], v150
	ds_read_b128 v[134:137], v150 offset:1024
	ds_read_b128 v[154:157], v150 offset:2048
	ds_read_b128 v[158:161], v150 offset:3072
	v_add_u32_e32 v150, s10, v147
	ds_read_b128 v[162:165], v150
	ds_read_b128 v[166:169], v150 offset:1024
	ds_read_b128 v[170:173], v150 offset:2048
	ds_read_b128 v[174:177], v150 offset:3072
	v_lshl_add_u64 v[150:151], s[20:21], 0, v[152:153]
	s_add_i32 m0, s48, 0xc000
	ds_read_b128 v[180:183], v149
	ds_read_b128 v[196:199], v149 offset:1024
	ds_read_b128 v[200:203], v149 offset:2048
	ds_read_b128 v[204:207], v149 offset:3072
	ds_read_b128 v[208:211], v149 offset:4096
	ds_read_b128 v[212:215], v149 offset:5120
	ds_read_b128 v[216:219], v149 offset:6144
	ds_read_b128 v[220:223], v149 offset:7168
	global_load_lds_dwordx4 v[150:151], off
	v_lshl_add_u64 v[150:151], s[20:21], 0, v[144:145]
	s_add_i32 m0, s48, 0xe000
	s_nop 0
	global_load_lds_dwordx4 v[150:151], off
	s_waitcnt vmcnt(8)
	s_waitcnt lgkmcnt(0)
	s_barrier
	s_setprio 1
	s_waitcnt lgkmcnt(0)
	v_mfma_f32_16x16x32_bf16 v[126:129], v[130:133], v[180:183], v[126:129]
	v_mfma_f32_16x16x32_bf16 v[122:125], v[154:157], v[180:183], v[122:125]
	v_mfma_f32_16x16x32_bf16 v[118:121], v[130:133], v[200:203], v[118:121]
	v_mfma_f32_16x16x32_bf16 v[114:117], v[154:157], v[200:203], v[114:117]
	v_mfma_f32_16x16x32_bf16 v[110:113], v[130:133], v[208:211], v[110:113]
	v_mfma_f32_16x16x32_bf16 v[106:109], v[154:157], v[208:211], v[106:109]
	v_mfma_f32_16x16x32_bf16 v[102:105], v[130:133], v[216:219], v[102:105]
	v_mfma_f32_16x16x32_bf16 v[98:101], v[154:157], v[216:219], v[98:101]
	v_mfma_f32_16x16x32_bf16 v[126:129], v[134:137], v[196:199], v[126:129]
	v_mfma_f32_16x16x32_bf16 v[122:125], v[158:161], v[196:199], v[122:125]
	v_mfma_f32_16x16x32_bf16 v[118:121], v[134:137], v[204:207], v[118:121]
	v_mfma_f32_16x16x32_bf16 v[114:117], v[158:161], v[204:207], v[114:117]
	v_mfma_f32_16x16x32_bf16 v[110:113], v[134:137], v[212:215], v[110:113]
	v_mfma_f32_16x16x32_bf16 v[106:109], v[158:161], v[212:215], v[106:109]
	v_mfma_f32_16x16x32_bf16 v[102:105], v[134:137], v[220:223], v[102:105]
	v_mfma_f32_16x16x32_bf16 v[98:101], v[158:161], v[220:223], v[98:101]
	s_setprio 0
	s_setprio 1
	v_mfma_f32_16x16x32_bf16 v[60:63], v[162:165], v[180:183], v[60:63]
	v_mfma_f32_16x16x32_bf16 v[56:59], v[170:173], v[180:183], v[56:59]
	v_mfma_f32_16x16x32_bf16 v[52:55], v[162:165], v[200:203], v[52:55]
	v_mfma_f32_16x16x32_bf16 v[48:51], v[170:173], v[200:203], v[48:51]
	v_mfma_f32_16x16x32_bf16 v[44:47], v[162:165], v[208:211], v[44:47]
	v_mfma_f32_16x16x32_bf16 v[40:43], v[170:173], v[208:211], v[40:43]
	v_mfma_f32_16x16x32_bf16 v[36:39], v[162:165], v[216:219], v[36:39]
	v_mfma_f32_16x16x32_bf16 v[32:35], v[170:173], v[216:219], v[32:35]
	v_mfma_f32_16x16x32_bf16 v[60:63], v[166:169], v[196:199], v[60:63]
	v_mfma_f32_16x16x32_bf16 v[56:59], v[174:177], v[196:199], v[56:59]
	v_mfma_f32_16x16x32_bf16 v[52:55], v[166:169], v[204:207], v[52:55]
	v_mfma_f32_16x16x32_bf16 v[48:51], v[174:177], v[204:207], v[48:51]
	v_mfma_f32_16x16x32_bf16 v[44:47], v[166:169], v[212:215], v[44:47]
	v_mfma_f32_16x16x32_bf16 v[40:43], v[174:177], v[212:215], v[40:43]
	v_mfma_f32_16x16x32_bf16 v[36:39], v[166:169], v[220:223], v[36:39]
	v_mfma_f32_16x16x32_bf16 v[32:35], v[174:177], v[220:223], v[32:35]
	s_setprio 0
	s_barrier
	s_add_i32 s11, vcc_hi, s41
	v_lshl_add_u64 v[150:151], s[78:79], 0, v[96:97]
	s_mov_b32 m0, s11
	ds_read_b128 v[180:183], v149 offset:16384
	ds_read_b128 v[196:199], v149 offset:17408
	ds_read_b128 v[200:203], v149 offset:18432
	ds_read_b128 v[204:207], v149 offset:19456
	ds_read_b128 v[208:211], v149 offset:20480
	ds_read_b128 v[212:215], v149 offset:21504
	ds_read_b128 v[216:219], v149 offset:22528
	ds_read_b128 v[220:223], v149 offset:23552
	global_load_lds_dwordx4 v[150:151], off
	s_add_i32 m0, s11, 0x2000
	v_lshl_add_u64 v[178:179], s[78:79], 0, v[142:143]
	s_add_u32 s78, s78, s6
	s_addc_u32 s79, s79, s7
	s_add_i32 s10, s10, s41
	global_load_lds_dwordx4 v[178:179], off
	v_lshl_add_u64 v[188:189], s[78:79], 0, v[96:97]
	s_mov_b32 m0, s10
	v_lshl_add_u64 v[194:195], s[78:79], 0, v[142:143]
	global_load_lds_dwordx4 v[188:189], off
	s_add_i32 m0, s10, 0x2000
	v_lshl_add_u64 v[224:225], s[22:23], 0, v[138:139]
	global_load_lds_dwordx4 v[194:195], off
	s_mov_b32 m0, s48
	v_lshl_add_u64 v[226:227], s[22:23], 0, v[140:141]
	global_load_lds_dwordx4 v[224:225], off
	s_mov_b32 m0, s49
	s_nop 0
	global_load_lds_dwordx4 v[226:227], off
	s_waitcnt vmcnt(8)
	s_waitcnt lgkmcnt(0)
	s_barrier
; #define PG8_STAGE(bufoff, gbase, voff) do { _Pragma("unroll") for (int _i = 0; _i < 2; ++_i) \
;         __builtin_amdgcn_global_load_lds((const unsigned*)((const char*)(gbase) + (voff)[_i]), (PG8_LAS unsigned*)(lds + (bufoff) + ldsw + _i * 8192), 16, 0, 0); } while (0)
; #define PG8_LDA(dst, b, h) do { _Pragma("unroll") for (int m = 0; m < 4; ++m) _Pragma("unroll") for (int k = 0; k < 2; ++k) dst[m][k] = *(const PG8_LAS bf16x8*)(lds + PG8_SA(b, h) + aoff + m * 2048 + k * 1024); } while (0)
; #define PG8_LDB(dst, b, h) do { _Pragma("unroll") for (int n = 0; n < 2; ++n) _Pragma("unroll") for (int k = 0; k < 2; ++k) dst[n][k] = *(const PG8_LAS bf16x8*)(lds + PG8_SB(b, h) + boff + n * 2048 + k * 1024); } while (0)
; #define PG8_MMA(ai, bj, At, Bt) do { __builtin_amdgcn_s_setprio(1); _Pragma("unroll") for (int m = 0; m < 4; ++m) _Pragma("unroll") for (int n = 0; n < 2; ++n) _Pragma("unroll") for (int k = 0; k < 2; ++k) \
;         acc[ai][bj][m][n] = __builtin_amdgcn_mfma_f32_16x16x32_bf16(Bt[n][k], At[m][k], acc[ai][bj][m][n], 0, 0, 0); __builtin_amdgcn_s_setprio(0); } while (0)
; #define PG8_WAIT_V(n) asm volatile("s_waitcnt vmcnt(" #n ")" ::: "memory")
; #define PG8_WAIT_L(n) asm volatile("s_waitcnt lgkmcnt(" #n ")" ::: "memory")
; #define PG8_BAR __builtin_amdgcn_s_barrier()
; #define PG8_SCHED __builtin_amdgcn_sched_barrier(0)
; template <class Epi, class Sched, bool ALIGN_EPI = false, bool SP2 = false>
; __device__ __forceinline__ void gemm_phase(PG8_LAS unsigned char* lds, const Gemm g, const Sched& S, const Epi& E, int wid_s_) {
;     ...
;             PG8_WAIT_V(8); PG8_WAIT_L(0); PG8_BAR; PG8_MMA(1, 0, At, B0); PG8_MMA(1, 1, At, B1); PG8_BAR; PG8_SCHED;
;             PG8_LDB(B0, 1, 0); PG8_LDB(B1, 1, 1); PG8_SCHED; PG8_LDA(At, 1, 0); PG8_STAGE(PG8_SA(0, 1), a2 + hstep, voffA);
;             PG8_WAIT_V(8); PG8_WAIT_L(0); PG8_BAR; PG8_MMA(0, 0, At, B0); PG8_MMA(0, 1, At, B1); PG8_BAR; PG8_SCHED;
	s_setprio 1
	s_waitcnt lgkmcnt(0)
	v_mfma_f32_16x16x32_bf16 v[92:95], v[130:133], v[180:183], v[92:95]
	v_mfma_f32_16x16x32_bf16 v[88:91], v[154:157], v[180:183], v[88:91]
	v_mfma_f32_16x16x32_bf16 v[84:87], v[130:133], v[200:203], v[84:87]
	v_mfma_f32_16x16x32_bf16 v[80:83], v[154:157], v[200:203], v[80:83]
	v_mfma_f32_16x16x32_bf16 v[76:79], v[130:133], v[208:211], v[76:79]
	v_mfma_f32_16x16x32_bf16 v[72:75], v[154:157], v[208:211], v[72:75]
	v_mfma_f32_16x16x32_bf16 v[68:71], v[130:133], v[216:219], v[68:71]
	v_mfma_f32_16x16x32_bf16 v[64:67], v[154:157], v[216:219], v[64:67]
	v_mfma_f32_16x16x32_bf16 v[92:95], v[134:137], v[196:199], v[92:95]
	v_mfma_f32_16x16x32_bf16 v[88:91], v[158:161], v[196:199], v[88:91]
	v_mfma_f32_16x16x32_bf16 v[84:87], v[134:137], v[204:207], v[84:87]
	v_mfma_f32_16x16x32_bf16 v[80:83], v[158:161], v[204:207], v[80:83]
	v_mfma_f32_16x16x32_bf16 v[76:79], v[134:137], v[212:215], v[76:79]
	v_mfma_f32_16x16x32_bf16 v[72:75], v[158:161], v[212:215], v[72:75]
	v_mfma_f32_16x16x32_bf16 v[68:71], v[134:137], v[220:223], v[68:71]
	v_mfma_f32_16x16x32_bf16 v[64:67], v[158:161], v[220:223], v[64:67]
	s_setprio 0
	s_setprio 1
	v_mfma_f32_16x16x32_bf16 v[28:31], v[162:165], v[180:183], v[28:31]
	v_mfma_f32_16x16x32_bf16 v[24:27], v[170:173], v[180:183], v[24:27]
	v_mfma_f32_16x16x32_bf16 v[20:23], v[162:165], v[200:203], v[20:23]
	v_mfma_f32_16x16x32_bf16 v[16:19], v[170:173], v[200:203], v[16:19]
	v_mfma_f32_16x16x32_bf16 v[12:15], v[162:165], v[208:211], v[12:15]
	v_mfma_f32_16x16x32_bf16 v[8:11], v[170:173], v[208:211], v[8:11]
	v_mfma_f32_16x16x32_bf16 v[4:7], v[162:165], v[216:219], v[4:7]
	v_mfma_f32_16x16x32_bf16 v[0:3], v[170:173], v[216:219], v[0:3]
	v_mfma_f32_16x16x32_bf16 v[28:31], v[166:169], v[196:199], v[28:31]
	v_mfma_f32_16x16x32_bf16 v[24:27], v[174:177], v[196:199], v[24:27]
	v_mfma_f32_16x16x32_bf16 v[20:23], v[166:169], v[204:207], v[20:23]
	v_mfma_f32_16x16x32_bf16 v[16:19], v[174:177], v[204:207], v[16:19]
	v_mfma_f32_16x16x32_bf16 v[12:15], v[166:169], v[212:215], v[12:15]
	v_mfma_f32_16x16x32_bf16 v[8:11], v[174:177], v[212:215], v[8:11]
	v_mfma_f32_16x16x32_bf16 v[4:7], v[166:169], v[220:223], v[4:7]
	v_mfma_f32_16x16x32_bf16 v[0:3], v[174:177], v[220:223], v[0:3]
	s_setprio 0
	s_barrier
	s_add_i32 s10, 16, 0x18000
	s_add_i32 s11, 16, 0x1c000
	v_add_u32_e32 v158, s10, v147
	v_add_u32_e32 v174, s11, v147
	ds_read_b128 v[130:133], v158
	ds_read_b128 v[134:137], v158 offset:1024
	ds_read_b128 v[154:157], v158 offset:2048
	ds_read_b128 v[158:161], v158 offset:3072
	ds_read_b128 v[162:165], v174
	ds_read_b128 v[166:169], v174 offset:1024
	ds_read_b128 v[170:173], v174 offset:2048
	ds_read_b128 v[174:177], v174 offset:3072
	s_add_u32 s22, s22, s6
	s_addc_u32 s23, s23, s7
	s_mov_b32 m0, s50
	v_lshl_add_u64 v[228:229], s[22:23], 0, v[138:139]
	ds_read_b128 v[180:183], v149 offset:32768
	ds_read_b128 v[196:199], v149 offset:33792
	ds_read_b128 v[200:203], v149 offset:34816
	ds_read_b128 v[204:207], v149 offset:35840
	ds_read_b128 v[208:211], v149 offset:36864
	ds_read_b128 v[212:215], v149 offset:37888
	ds_read_b128 v[216:219], v149 offset:38912
	ds_read_b128 v[220:223], v149 offset:39936
	global_load_lds_dwordx4 v[228:229], off
	v_lshl_add_u64 v[228:229], s[22:23], 0, v[140:141]
	s_mov_b32 m0, s51
	s_nop 0
	global_load_lds_dwordx4 v[228:229], off
	s_waitcnt vmcnt(8)
	s_waitcnt lgkmcnt(0)
	s_barrier
	s_setprio 1
	s_waitcnt lgkmcnt(0)
	v_mfma_f32_16x16x32_bf16 v[126:129], v[130:133], v[180:183], v[126:129]
	v_mfma_f32_16x16x32_bf16 v[122:125], v[154:157], v[180:183], v[122:125]
	v_mfma_f32_16x16x32_bf16 v[118:121], v[130:133], v[200:203], v[118:121]
	v_mfma_f32_16x16x32_bf16 v[114:117], v[154:157], v[200:203], v[114:117]
	v_mfma_f32_16x16x32_bf16 v[110:113], v[130:133], v[208:211], v[110:113]
	v_mfma_f32_16x16x32_bf16 v[106:109], v[154:157], v[208:211], v[106:109]
	v_mfma_f32_16x16x32_bf16 v[102:105], v[130:133], v[216:219], v[102:105]
	v_mfma_f32_16x16x32_bf16 v[98:101], v[154:157], v[216:219], v[98:101]
	v_mfma_f32_16x16x32_bf16 v[126:129], v[134:137], v[196:199], v[126:129]
	v_mfma_f32_16x16x32_bf16 v[122:125], v[158:161], v[196:199], v[122:125]
	v_mfma_f32_16x16x32_bf16 v[118:121], v[134:137], v[204:207], v[118:121]
	v_mfma_f32_16x16x32_bf16 v[114:117], v[158:161], v[204:207], v[114:117]
	v_mfma_f32_16x16x32_bf16 v[110:113], v[134:137], v[212:215], v[110:113]
	v_mfma_f32_16x16x32_bf16 v[106:109], v[158:161], v[212:215], v[106:109]
	v_mfma_f32_16x16x32_bf16 v[102:105], v[134:137], v[220:223], v[102:105]
	v_mfma_f32_16x16x32_bf16 v[98:101], v[158:161], v[220:223], v[98:101]
	s_setprio 0
	s_setprio 1
	v_mfma_f32_16x16x32_bf16 v[60:63], v[162:165], v[180:183], v[60:63]
	v_mfma_f32_16x16x32_bf16 v[56:59], v[170:173], v[180:183], v[56:59]
	v_mfma_f32_16x16x32_bf16 v[52:55], v[162:165], v[200:203], v[52:55]
	v_mfma_f32_16x16x32_bf16 v[48:51], v[170:173], v[200:203], v[48:51]
	v_mfma_f32_16x16x32_bf16 v[44:47], v[162:165], v[208:211], v[44:47]
	v_mfma_f32_16x16x32_bf16 v[40:43], v[170:173], v[208:211], v[40:43]
	v_mfma_f32_16x16x32_bf16 v[36:39], v[162:165], v[216:219], v[36:39]
	v_mfma_f32_16x16x32_bf16 v[32:35], v[170:173], v[216:219], v[32:35]
	v_mfma_f32_16x16x32_bf16 v[60:63], v[166:169], v[196:199], v[60:63]
	v_mfma_f32_16x16x32_bf16 v[56:59], v[174:177], v[196:199], v[56:59]
	v_mfma_f32_16x16x32_bf16 v[52:55], v[166:169], v[204:207], v[52:55]
	v_mfma_f32_16x16x32_bf16 v[48:51], v[174:177], v[204:207], v[48:51]
	v_mfma_f32_16x16x32_bf16 v[44:47], v[166:169], v[212:215], v[44:47]
	v_mfma_f32_16x16x32_bf16 v[40:43], v[174:177], v[212:215], v[40:43]
	v_mfma_f32_16x16x32_bf16 v[36:39], v[166:169], v[220:223], v[36:39]
	v_mfma_f32_16x16x32_bf16 v[32:35], v[174:177], v[220:223], v[32:35]
	s_setprio 0
	s_barrier
; #define PG8_STAGE(bufoff, gbase, voff) do { _Pragma("unroll") for (int _i = 0; _i < 2; ++_i) \
;         __builtin_amdgcn_global_load_lds((const unsigned*)((const char*)(gbase) + (voff)[_i]), (PG8_LAS unsigned*)(lds + (bufoff) + ldsw + _i * 8192), 16, 0, 0); } while (0)
; #define PG8_LDA(dst, b, h) do { _Pragma("unroll") for (int m = 0; m < 4; ++m) _Pragma("unroll") for (int k = 0; k < 2; ++k) dst[m][k] = *(const PG8_LAS bf16x8*)(lds + PG8_SA(b, h) + aoff + m * 2048 + k * 1024); } while (0)
; #define PG8_MMA(ai, bj, At, Bt) do { __builtin_amdgcn_s_setprio(1); _Pragma("unroll") for (int m = 0; m < 4; ++m) _Pragma("unroll") for (int n = 0; n < 2; ++n) _Pragma("unroll") for (int k = 0; k < 2; ++k) \
;         acc[ai][bj][m][n] = __builtin_amdgcn_mfma_f32_16x16x32_bf16(Bt[n][k], At[m][k], acc[ai][bj][m][n], 0, 0, 0); __builtin_amdgcn_s_setprio(0); } while (0)
; #define PG8_WAIT_V(n) asm volatile("s_waitcnt vmcnt(" #n ")" ::: "memory")
; #define PG8_WAIT_L(n) asm volatile("s_waitcnt lgkmcnt(" #n ")" ::: "memory")
; #define PG8_BAR __builtin_amdgcn_s_barrier()
; #define PG8_SCHED __builtin_amdgcn_sched_barrier(0)
; template <class Epi, class Sched, bool ALIGN_EPI = false, bool SP2 = false>
; __device__ __forceinline__ void gemm_phase(PG8_LAS unsigned char* lds, const Gemm g, const Sched& S, const Epi& E, int wid_s_) {
;     ...
;         for (int t = 0; t < nt; t += 2) {
;     ...
;             PG8_LDA(At, 1, 1); PG8_STAGE(PG8_SB(1, 0), b3, voffB); PG8_STAGE(PG8_SB(1, 1), b3 + hstep, voffB); PG8_STAGE(PG8_SA(1, 0), a3, voffA);
;             PG8_WAIT_V(8); PG8_WAIT_L(0); PG8_BAR; PG8_MMA(1, 0, At, B0); PG8_MMA(1, 1, At, B1); PG8_BAR; PG8_SCHED;
	s_add_i32 s10, s10, s41
	v_lshl_add_u64 v[150:151], v[150:151], 0, s[42:43]
	s_mov_b32 m0, s10
	ds_read_b128 v[180:183], v149 offset:49152
	ds_read_b128 v[196:199], v149 offset:50176
	ds_read_b128 v[200:203], v149 offset:51200
	ds_read_b128 v[204:207], v149 offset:52224
	ds_read_b128 v[208:211], v149 offset:53248
	ds_read_b128 v[212:215], v149 offset:54272
	ds_read_b128 v[216:219], v149 offset:55296
	ds_read_b128 v[220:223], v149 offset:56320
	global_load_lds_dwordx4 v[150:151], off
	v_lshl_add_u64 v[150:151], v[178:179], 0, s[42:43]
	s_add_i32 m0, s10, 0x2000
	s_add_i32 s10, s11, s41
	global_load_lds_dwordx4 v[150:151], off
	v_lshl_add_u64 v[150:151], v[188:189], 0, s[42:43]
	s_mov_b32 m0, s10
	s_nop 0
	global_load_lds_dwordx4 v[150:151], off
	v_lshl_add_u64 v[150:151], v[194:195], 0, s[42:43]
	s_add_i32 m0, s10, 0x2000
	s_nop 0
	global_load_lds_dwordx4 v[150:151], off
	v_lshl_add_u64 v[150:151], v[224:225], 0, s[42:43]
	s_mov_b32 m0, s81
	s_nop 0
	global_load_lds_dwordx4 v[150:151], off
	v_lshl_add_u64 v[150:151], v[226:227], 0, s[42:43]
	s_mov_b32 m0, s82
	s_nop 0
	global_load_lds_dwordx4 v[150:151], off
	s_waitcnt vmcnt(8)
	s_waitcnt lgkmcnt(0)
	s_barrier
	s_setprio 1
	s_waitcnt lgkmcnt(0)
	v_mfma_f32_16x16x32_bf16 v[92:95], v[130:133], v[180:183], v[92:95]
	v_mfma_f32_16x16x32_bf16 v[88:91], v[154:157], v[180:183], v[88:91]
	v_mfma_f32_16x16x32_bf16 v[84:87], v[130:133], v[200:203], v[84:87]
	v_mfma_f32_16x16x32_bf16 v[80:83], v[154:157], v[200:203], v[80:83]
	v_mfma_f32_16x16x32_bf16 v[76:79], v[130:133], v[208:211], v[76:79]
	v_mfma_f32_16x16x32_bf16 v[72:75], v[154:157], v[208:211], v[72:75]
	v_mfma_f32_16x16x32_bf16 v[68:71], v[130:133], v[216:219], v[68:71]
	v_mfma_f32_16x16x32_bf16 v[64:67], v[154:157], v[216:219], v[64:67]
	v_mfma_f32_16x16x32_bf16 v[92:95], v[134:137], v[196:199], v[92:95]
	v_mfma_f32_16x16x32_bf16 v[88:91], v[158:161], v[196:199], v[88:91]
	v_mfma_f32_16x16x32_bf16 v[84:87], v[134:137], v[204:207], v[84:87]
	v_mfma_f32_16x16x32_bf16 v[80:83], v[158:161], v[204:207], v[80:83]
	v_mfma_f32_16x16x32_bf16 v[76:79], v[134:137], v[212:215], v[76:79]
	v_mfma_f32_16x16x32_bf16 v[72:75], v[158:161], v[212:215], v[72:75]
	v_mfma_f32_16x16x32_bf16 v[68:71], v[134:137], v[220:223], v[68:71]
	v_mfma_f32_16x16x32_bf16 v[64:67], v[158:161], v[220:223], v[64:67]
	s_setprio 0
	s_setprio 1
	v_mfma_f32_16x16x32_bf16 v[28:31], v[162:165], v[180:183], v[28:31]
	v_mfma_f32_16x16x32_bf16 v[24:27], v[170:173], v[180:183], v[24:27]
	v_mfma_f32_16x16x32_bf16 v[20:23], v[162:165], v[200:203], v[20:23]
	v_mfma_f32_16x16x32_bf16 v[16:19], v[170:173], v[200:203], v[16:19]
	v_mfma_f32_16x16x32_bf16 v[12:15], v[162:165], v[208:211], v[12:15]
	v_mfma_f32_16x16x32_bf16 v[8:11], v[170:173], v[208:211], v[8:11]
	v_mfma_f32_16x16x32_bf16 v[4:7], v[162:165], v[216:219], v[4:7]
	v_mfma_f32_16x16x32_bf16 v[0:3], v[170:173], v[216:219], v[0:3]
	v_mfma_f32_16x16x32_bf16 v[28:31], v[166:169], v[196:199], v[28:31]
	v_mfma_f32_16x16x32_bf16 v[24:27], v[174:177], v[196:199], v[24:27]
	v_mfma_f32_16x16x32_bf16 v[20:23], v[166:169], v[204:207], v[20:23]
	v_mfma_f32_16x16x32_bf16 v[16:19], v[174:177], v[204:207], v[16:19]
	v_mfma_f32_16x16x32_bf16 v[12:15], v[166:169], v[212:215], v[12:15]
	v_mfma_f32_16x16x32_bf16 v[8:11], v[174:177], v[212:215], v[8:11]
	v_mfma_f32_16x16x32_bf16 v[4:7], v[166:169], v[220:223], v[4:7]
	v_mfma_f32_16x16x32_bf16 v[0:3], v[174:177], v[220:223], v[0:3]
	s_setprio 0
	s_barrier
	s_add_u32 s90, s90, 0x100
	s_addc_u32 s91, s91, 0
	s_add_u32 s20, s20, 0x100
	s_addc_u32 s21, s21, 0
	s_cmp_ge_i32 vcc_lo, s80
	s_mov_b32 s22, vcc_lo
	s_cbranch_scc0 .LBB0_1393
